# K_FFN epilogue: row-neighbour exchange via DPP row_ror instead of ds_bpermute (on top of clean MFMA segments)
# baseline (speedup 1.0000x reference)
;     __device__ __forceinline__ void operator()(const f32x4 (&acc)[2][2][4][2], const GUnit& u, int wr, int wc, int fr, int fq, LAS unsigned char* lds) const {
;     ...
;                         for (int q = 0; q < 2; ++q) gp[m][2 * n + q] = pk_f16(acc[ai][1][m][n][2 * q], acc[ai][1][m][n][2 * q + 1]);
; #pragma unroll
;                 for (int n = 0; n < 2; ++n) {
;                     const f32x4 eu = c > 0 ? *(const LAS f32x4*)(EL + ((c - 1) * 2 + 1) * 128 + wc * 32 + 8 * fqL + 4 * n) : (f32x4){0.f, 0.f, 0.f, 0.f};
;                     const f32x4 ed = c < 3 ? *(const LAS f32x4*)(EL + ((c + 1) * 2 + 0) * 128 + wc * 32 + 8 * fqL + 4 * n) : (f32x4){0.f, 0.f, 0.f, 0.f};
; #pragma unroll
;                     for (int q = 0; q < 2; ++q) { eup[2 * n + q] = pk_f16(eu[2 * q], eu[2 * q + 1]); edp[2 * n + q] = pk_f16(ed[2 * q], ed[2 * q + 1]); } }
; #pragma unroll
;                 for (int m = 0; m < 4; ++m) {
;                     u32x4 UP, DN, GG;
; #pragma unroll
;                     for (int j = 0; j < 4; ++j) { const int g = (int)gp[m][j];
;                         const int oldu = m > 0 ? shl_((int)gp[m > 0 ? m - 1 : 0][j], lane15) : (int)eup[j];
;                         const int ups = __builtin_amdgcn_update_dpp(0, g, 0x111, 0xf, 0xf, true);
;                         const int oldd = m < 3 ? shl_((int)gp[m < 3 ? m + 1 : 3][j], lane0r) : (int)edp[j];
;                         const int dns = __builtin_amdgcn_update_dpp(0, g, 0x101, 0xf, 0xf, true);
;                         UP[j] = (unsigned)(frL == 0 ? oldu : ups); DN[j] = (unsigned)(frL == 15 ? oldd : dns); GG[j] = (unsigned)g; }
;                     const f16x8 uph = __builtin_bit_cast(f16x8, UP), dnh = __builtin_bit_cast(f16x8, DN), ggh = __builtin_bit_cast(f16x8, GG);
;                     f16x2 yv[4];
;                     yv[0] = __builtin_shufflevector(uph, uph, 0, 1) * w0p[0] + __builtin_shufflevector(ggh, ggh, 0, 1) * w1p[0] + __builtin_shufflevector(dnh, dnh, 0, 1) * w2p[0] + bbp[0];
;                     yv[1] = __builtin_shufflevector(uph, uph, 2, 3) * w0p[1] + __builtin_shufflevector(ggh, ggh, 2, 3) * w1p[1] + __builtin_shufflevector(dnh, dnh, 2, 3) * w2p[1] + bbp[1];
;                     yv[2] = __builtin_shufflevector(uph, uph, 4, 5) * w0p[2] + __builtin_shufflevector(ggh, ggh, 4, 5) * w1p[2] + __builtin_shufflevector(dnh, dnh, 4, 5) * w2p[2] + bbp[2];
.LBB0_264:
	s_waitcnt vmcnt(0)
	v_cvt_pk_f16_f32 v164, v164, v165
	v_cvt_pk_f16_f32 v156, v156, v157
	v_cvt_pk_f16_f32 v157, v142, v143
	v_lshlrev_b32_e32 v165, 6, v183
	v_cvt_pk_f16_f32 v142, v106, v107
	v_cvt_pk_f16_f32 v162, v162, v163
	v_cvt_pk_f16_f32 v163, v148, v149
	v_mov_b32_dpp v149, v142 row_ror:15 row_mask:0xf bank_mask:0xf
	v_cvt_pk_f16_f32 v170, v170, v171
	v_cvt_pk_f16_f32 v171, v122, v123
	v_cvt_pk_f16_f32 v160, v160, v161
	v_cvt_pk_f16_f32 v158, v158, v159
	v_cvt_pk_f16_f32 v161, v150, v151
	v_cvt_pk_f16_f32 v159, v140, v141
	v_cvt_pk_f16_f32 v143, v104, v105
	v_cvt_pk_f16_f32 v141, v100, v101
	v_cmp_eq_u32_e64 s[8:9], 15, v32
	v_mov_b32_dpp v150, v171 row_shl:1 row_mask:0xf bank_mask:0xf bound_ctrl:1
	v_cvt_pk_f16_f32 v152, v152, v153
	v_cvt_pk_f16_f32 v153, v146, v147
	v_mov_b32_dpp v147, v143 row_ror:15 row_mask:0xf bank_mask:0xf
	s_waitcnt lgkmcnt(0)
	v_cndmask_b32_e64 v149, v150, v149, s[8:9]
	v_mov_b32_dpp v150, v141 row_ror:15 row_mask:0xf bank_mask:0xf
	v_cvt_pk_f16_f32 v168, v168, v169
	v_cvt_pk_f16_f32 v169, v116, v117
	v_cvt_pk_f16_f32 v173, v172, v173
	v_cvt_pk_f16_f32 v154, v154, v155
	v_cvt_pk_f16_f32 v155, v144, v145
	v_cvt_pk_f16_f32 v172, v120, v121
	v_cvt_pk_f16_f32 v140, v102, v103
	v_cvt_pk_f16_f32 v144, v176, v177
	v_cmp_eq_u32_e64 s[10:11], 0, v32
	v_mov_b32_dpp v151, v169 row_shr:1 row_mask:0xf bank_mask:0xf bound_ctrl:1
	v_mov_b32_dpp v146, v172 row_shr:1 row_mask:0xf bank_mask:0xf bound_ctrl:1
	v_cndmask_b32_e64 v144, v151, v144, s[10:11]
	v_mov_b32_dpp v151, v140 row_ror:15 row_mask:0xf bank_mask:0xf
	v_cvt_pk_f16_f32 v166, v166, v167
	v_cvt_pk_f16_f32 v167, v118, v119
	v_mov_b32_dpp v148, v172 row_shl:1 row_mask:0xf bank_mask:0xf bound_ctrl:1
	v_cndmask_b32_e64 v146, v146, v173, s[10:11]
	v_mov_b32_dpp v173, v169 row_shl:1 row_mask:0xf bank_mask:0xf bound_ctrl:1
	v_cvt_pk_f16_f32 v174, v174, v175
	v_cvt_pk_f16_f32 v145, v178, v179
	v_cndmask_b32_e64 v147, v148, v147, s[8:9]
	v_mov_b32_dpp v148, v171 row_shr:1 row_mask:0xf bank_mask:0xf bound_ctrl:1
	s_waitcnt lgkmcnt(0)
	v_cndmask_b32_e64 v150, v173, v150, s[8:9]
	v_mov_b32_dpp v173, v167 row_shr:1 row_mask:0xf bank_mask:0xf bound_ctrl:1
	v_cndmask_b32_e64 v148, v148, v174, s[10:11]
	v_cndmask_b32_e64 v145, v173, v145, s[10:11]
	v_mov_b32_dpp v174, v167 row_shl:1 row_mask:0xf bank_mask:0xf bound_ctrl:1
	v_pk_mul_f16 v146, v164, v146
	v_pk_mul_f16 v148, v166, v148
	v_pk_mul_f16 v145, v170, v145
	s_waitcnt lgkmcnt(0)
	v_cndmask_b32_e64 v151, v174, v151, s[8:9]
	v_pk_fma_f16 v145, v162, v167, v145
	v_pk_fma_f16 v148, v158, v171, v148
	v_pk_fma_f16 v146, v156, v172, v146
	s_and_b32 s36, s37, 7
	v_pk_mul_f16 v144, v168, v144
	v_pk_fma_f16 v146, v163, v147, v146
	v_pk_fma_f16 v147, v161, v149, v148
	v_pk_fma_f16 v145, v154, v151, v145
	v_readlane_b32 s45, v251, 56
	s_cmp_eq_u32 s36, 0
	v_pk_fma_f16 v144, v160, v169, v144
	v_pk_add_f16 v173, v153, v145
	v_pk_add_f16 v145, v157, v147
	v_or_b32_e32 v147, s45, v32
	s_cselect_b64 s[12:13], -1, 0
	v_pk_fma_f16 v144, v152, v150, v144
	v_cmp_ne_u32_e32 vcc, 0, v147
	v_pk_add_f16 v144, v155, v144
	v_pk_add_f16 v146, v159, v146
	s_or_b64 s[12:13], vcc, s[12:13]
	s_and_saveexec_b64 s[68:69], s[12:13]
	s_xor_b64 s[72:73], exec, s[68:69]
	s_andn2_saveexec_b64 s[72:73], s[72:73]
	s_cbranch_execz .LBB0_266
	s_lshl_b32 s45, s37, 1
	v_mov_b32_e32 v147, 0xb00
	v_mad_i64_i32 v[148:149], s[68:69], s45, v147, v[190:191]
	v_readlane_b32 s68, v251, 22
	v_lshlrev_b64 v[148:149], 2, v[148:149]
	v_readlane_b32 s69, v251, 23
	v_cvt_f32_f16_sdwa v151, v146 dst_sel:DWORD dst_unused:UNUSED_PAD src0_sel:WORD_1
	v_cvt_f32_f16_e32 v150, v146
	v_lshl_add_u64 v[174:175], s[68:69], 0, v[148:149]
	v_readlane_b32 s68, v251, 24
	v_readlane_b32 s69, v251, 25
	global_store_dwordx2 v[174:175], v[120:121], off
	s_nop 0
	v_lshl_add_u64 v[174:175], s[68:69], 0, v[148:149]
	v_readlane_b32 s68, v251, 26
	v_readlane_b32 s69, v251, 27
	global_store_dwordx2 v[174:175], v[150:151], off
	s_nop 0
	v_lshl_add_u64 v[148:149], s[68:69], 0, v[148:149]
	global_store_dwordx2 v[148:149], v[128:129], off

;     __device__ __forceinline__ void operator()(const f32x4 (&acc)[2][2][4][2], const GUnit& u, int wr, int wc, int fr, int fq, LAS unsigned char* lds) const {
;     ...
;                     for (int j = 0; j < 4; ++j) { const int g = (int)gp[m][j];
;                         const int oldu = m > 0 ? shl_((int)gp[m > 0 ? m - 1 : 0][j], lane15) : (int)eup[j];
;                         const int ups = __builtin_amdgcn_update_dpp(0, g, 0x111, 0xf, 0xf, true);
;                         const int oldd = m < 3 ? shl_((int)gp[m < 3 ? m + 1 : 3][j], lane0r) : (int)edp[j];
;                         const int dns = __builtin_amdgcn_update_dpp(0, g, 0x101, 0xf, 0xf, true);
;                         UP[j] = (unsigned)(frL == 0 ? oldu : ups); DN[j] = (unsigned)(frL == 15 ? oldd : dns); GG[j] = (unsigned)g; }
;                     const f16x8 uph = __builtin_bit_cast(f16x8, UP), dnh = __builtin_bit_cast(f16x8, DN), ggh = __builtin_bit_cast(f16x8, GG);
;                     f16x2 yv[4];
;                     yv[0] = __builtin_shufflevector(uph, uph, 0, 1) * w0p[0] + __builtin_shufflevector(ggh, ggh, 0, 1) * w1p[0] + __builtin_shufflevector(dnh, dnh, 0, 1) * w2p[0] + bbp[0];
;                     yv[1] = __builtin_shufflevector(uph, uph, 2, 3) * w0p[1] + __builtin_shufflevector(ggh, ggh, 2, 3) * w1p[1] + __builtin_shufflevector(dnh, dnh, 2, 3) * w2p[1] + bbp[1];
;                     yv[2] = __builtin_shufflevector(uph, uph, 4, 5) * w0p[2] + __builtin_shufflevector(ggh, ggh, 4, 5) * w1p[2] + __builtin_shufflevector(dnh, dnh, 4, 5) * w2p[2] + bbp[2];
;                     yv[3] = __builtin_shufflevector(uph, uph, 6, 7) * w0p[3] + __builtin_shufflevector(ggh, ggh, 6, 7) * w1p[3] + __builtin_shufflevector(dnh, dnh, 6, 7) * w2p[3] + bbp[3];
;                     u32x4 o;
; #pragma unroll
;                     for (int n = 0; n < 2; ++n)
; #pragma unroll
;                         for (int q = 0; q < 2; ++q) { const int j = 2 * n + q;
;                             if (m == 0 && c == 0 && frL == 0 && pmod != 0) { const size_t off = (size_t)(u.pm * 2 + 0) * DFF + fb + 4 * n + 2 * q; *(f32x2*)(GB + off) = (f32x2){acc[ai][1][0][n][2 * q], acc[ai][1][0][n][2 * q + 1]}; *(f32x2*)(YP + off) = (f32x2){(float)yv[j][0], (float)yv[j][1]}; *(f32x2*)(VB + off) = (f32x2){acc[ai][0][0][n][2 * q], acc[ai][0][0][n][2 * q + 1]}; }
.LBB0_272:
	s_or_b64 exec, exec, s[12:13]
	v_and_b32_e32 v150, 0x7fff7fff, v146
	s_movk_i32 s45, 0x336a
	v_pk_fma_f16 v151, v150, s45, 1.0 op_sel_hi:[1,0,0]
	s_movk_i32 s55, 0x383f
	v_rcp_f16_e32 v174, v151
	v_rcp_f16_sdwa v151, v151 dst_sel:DWORD dst_unused:UNUSED_PAD src0_sel:WORD_1
	s_movk_i32 s65, 0x39b0
	s_mov_b32 s68, 0xb08d
	s_movk_i32 s69, 0x3014
	v_pack_b32_f16 v151, v174, v151
	v_pk_fma_f16 v174, v151, s55, v228 op_sel_hi:[1,0,0]
	s_mov_b32 s72, 0xb9c5
	v_pk_fma_f16 v174, v151, v174, s65 op_sel_hi:[1,1,0]
	v_cvt_pk_f16_f32 v147, v128, v129
	v_pk_fma_f16 v174, v151, v174, s68 op_sel_hi:[1,1,0]
	v_pk_mul_f16 v175, v145, v145
	v_pk_fma_f16 v174, v151, v174, s69 op_sel_hi:[1,1,0]
	v_and_b32_e32 v179, 0x7fff7fff, v173
	v_pk_mul_f16 v151, v151, v174
	v_pk_mul_f16 v174, v146, v146
	v_pk_max_f16 v146, v146, v146
	v_pk_mul_f16 v174, v174, s72 op_sel_hi:[1,0]
	v_pk_max_f16 v146, v146, 0
	v_exp_f16_e32 v178, v174
	v_exp_f16_sdwa v174, v174 dst_sel:DWORD dst_unused:UNUSED_PAD src0_sel:WORD_1
	v_pk_fma_f16 v183, v179, s45, 1.0 op_sel_hi:[1,0,0]
	v_pk_mul_f16 v177, v173, v173
	v_rcp_f16_e32 v189, v183
	v_pack_b32_f16 v174, v178, v174
	v_pk_mul_f16 v151, v174, v151
	v_rcp_f16_sdwa v183, v183 dst_sel:DWORD dst_unused:UNUSED_PAD src0_sel:WORD_1
	v_pk_fma_f16 v146, v150, v151, v146 neg_lo:[1,0,0] neg_hi:[1,0,0]
	v_pk_mul_f16 v176, v144, v144
	v_pk_mul_f16 v146, v147, v146
	v_and_b32_e32 v147, 0x7fff7fff, v145
	v_pk_fma_f16 v150, v147, s45, 1.0 op_sel_hi:[1,0,0]
	v_pk_max_f16 v145, v145, v145
	v_rcp_f16_e32 v151, v150
	v_rcp_f16_sdwa v150, v150 dst_sel:DWORD dst_unused:UNUSED_PAD src0_sel:WORD_1
	v_add_u32_e32 v146, 0x40004, v146
	v_pk_max_f16 v145, v145, 0
	v_and_b32_e32 v174, 0xfff8fff8, v146
	v_pack_b32_f16 v150, v151, v150
	v_pk_fma_f16 v151, v150, s55, v228 op_sel_hi:[1,0,0]
	v_cvt_pk_f16_f32 v146, v130, v131
	v_pk_fma_f16 v151, v150, v151, s65 op_sel_hi:[1,1,0]
	v_pack_b32_f16 v183, v189, v183
	v_pk_fma_f16 v151, v150, v151, s68 op_sel_hi:[1,1,0]
	v_pk_fma_f16 v189, v183, s55, v228 op_sel_hi:[1,0,0]
	v_pk_fma_f16 v151, v150, v151, s69 op_sel_hi:[1,1,0]
	v_pk_fma_f16 v189, v183, v189, s65 op_sel_hi:[1,1,0]
	v_pk_mul_f16 v150, v150, v151
	v_pk_mul_f16 v151, v175, s72 op_sel_hi:[1,0]
	v_pk_fma_f16 v189, v183, v189, s68 op_sel_hi:[1,1,0]
	v_exp_f16_e32 v175, v151
	v_exp_f16_sdwa v151, v151 dst_sel:DWORD dst_unused:UNUSED_PAD src0_sel:WORD_1
	v_pk_fma_f16 v189, v183, v189, s69 op_sel_hi:[1,1,0]
	v_pk_mul_f16 v177, v177, s72 op_sel_hi:[1,0]
	v_pk_mul_f16 v183, v183, v189
	v_pack_b32_f16 v151, v175, v151
	v_pk_mul_f16 v150, v151, v150
	v_exp_f16_e32 v189, v177
	v_pk_fma_f16 v145, v147, v150, v145 neg_lo:[1,0,0] neg_hi:[1,0,0]
	v_exp_f16_sdwa v177, v177 dst_sel:DWORD dst_unused:UNUSED_PAD src0_sel:WORD_1
	v_pk_mul_f16 v145, v146, v145
	v_and_b32_e32 v146, 0x7fff7fff, v144
	v_pk_fma_f16 v147, v146, s45, 1.0 op_sel_hi:[1,0,0]
	v_pk_max_f16 v144, v144, v144
	v_rcp_f16_e32 v150, v147
	v_rcp_f16_sdwa v147, v147 dst_sel:DWORD dst_unused:UNUSED_PAD src0_sel:WORD_1
	v_pack_b32_f16 v177, v189, v177
	v_pk_max_f16 v173, v173, v173
	v_add_u32_e32 v145, 0x40004, v145
	v_pack_b32_f16 v147, v150, v147
	v_pk_fma_f16 v150, v147, s55, v228 op_sel_hi:[1,0,0]
	v_pk_max_f16 v144, v144, 0
	v_pk_fma_f16 v150, v147, v150, s65 op_sel_hi:[1,1,0]
	v_pk_max_f16 v173, v173, 0
	v_pk_fma_f16 v150, v147, v150, s68 op_sel_hi:[1,1,0]
	v_pk_mul_f16 v177, v177, v183
	v_pk_fma_f16 v150, v147, v150, s69 op_sel_hi:[1,1,0]
	v_and_b32_e32 v175, 0xfff8fff8, v145
	v_pk_mul_f16 v147, v147, v150
	v_pk_mul_f16 v150, v176, s72 op_sel_hi:[1,0]
	v_cvt_pk_f16_f32 v145, v124, v125
	v_exp_f16_e32 v151, v150
	v_exp_f16_sdwa v150, v150 dst_sel:DWORD dst_unused:UNUSED_PAD src0_sel:WORD_1
	s_cmp_lg_u32 s36, 7
	v_readlane_b32 s12, v253, 13
	v_cvt_pk_f16_f32 v178, v126, v127
	v_pack_b32_f16 v150, v151, v150
	v_pk_mul_f16 v147, v150, v147
	v_pk_fma_f16 v173, v179, v177, v173 neg_lo:[1,0,0] neg_hi:[1,0,0]
	v_pk_fma_f16 v144, v146, v147, v144 neg_lo:[1,0,0] neg_hi:[1,0,0]
	s_cselect_b64 s[80:81], -1, 0
	v_pk_mul_f16 v144, v145, v144
	s_add_i32 s29, s29, s48
	v_readlane_b32 s13, v253, 14
	v_pk_mul_f16 v173, v178, v173
	v_add_u32_e32 v144, 0x40004, v144
	v_add_u32_e32 v32, s29, v32
	v_lshl_add_u64 v[150:151], v[190:191], 1, s[12:13]
	v_add_u32_e32 v173, 0x40004, v173
	s_movk_i32 s29, 0x1600
	v_and_b32_e32 v176, 0xfff8fff8, v144
	v_cvt_pk_f16_f32 v147, v88, v89
	v_and_b32_e32 v177, 0xfff8fff8, v173
	v_mad_i64_i32 v[178:179], s[12:13], v32, s29, v[150:151]
	global_store_dwordx4 v[178:179], v[174:177], off
	v_mov_b32_dpp v172, v172 row_ror:1 row_mask:0xf bank_mask:0xf
	s_nop 0
	v_mov_b32_dpp v174, v147 row_ror:15 row_mask:0xf bank_mask:0xf
	v_cvt_pk_f16_f32 v146, v90, v91
	v_mov_b32_dpp v173, v143 row_shr:1 row_mask:0xf bank_mask:0xf bound_ctrl:1
	v_mov_b32_dpp v175, v143 row_shl:1 row_mask:0xf bank_mask:0xf bound_ctrl:1
	s_waitcnt lgkmcnt(0)
	v_cndmask_b32_e64 v172, v173, v172, s[10:11]
	s_waitcnt lgkmcnt(0)
	v_cndmask_b32_e64 v173, v175, v174, s[8:9]
	v_mov_b32_dpp v171, v171 row_ror:1 row_mask:0xf bank_mask:0xf
	v_mov_b32_dpp v175, v146 row_ror:15 row_mask:0xf bank_mask:0xf
	v_cvt_pk_f16_f32 v144, v84, v85
	v_mov_b32_dpp v174, v142 row_shr:1 row_mask:0xf bank_mask:0xf bound_ctrl:1
	v_mov_b32_dpp v176, v142 row_shl:1 row_mask:0xf bank_mask:0xf bound_ctrl:1
	s_waitcnt lgkmcnt(0)
	v_cndmask_b32_e64 v171, v174, v171, s[10:11]
	s_waitcnt lgkmcnt(0)
	v_cndmask_b32_e64 v174, v176, v175, s[8:9]
	v_mov_b32_dpp v169, v169 row_ror:1 row_mask:0xf bank_mask:0xf
	v_mov_b32_dpp v176, v144 row_ror:15 row_mask:0xf bank_mask:0xf
	v_mov_b32_dpp v167, v167 row_ror:1 row_mask:0xf bank_mask:0xf
	v_cvt_pk_f16_f32 v137, v136, v137
	v_cvt_pk_f16_f32 v136, v138, v139
	v_cvt_pk_f16_f32 v138, v86, v87
	v_mov_b32_dpp v175, v141 row_shr:1 row_mask:0xf bank_mask:0xf bound_ctrl:1
	v_mov_b32_dpp v177, v141 row_shl:1 row_mask:0xf bank_mask:0xf bound_ctrl:1
	s_waitcnt lgkmcnt(0)
;     __device__ __forceinline__ void operator()(const f32x4 (&acc)[2][2][4][2], const GUnit& u, int wr, int wc, int fr, int fq, LAS unsigned char* lds) const {
;     ...
;                     for (int j = 0; j < 4; ++j) { const int g = (int)gp[m][j];
;                         const int oldu = m > 0 ? shl_((int)gp[m > 0 ? m - 1 : 0][j], lane15) : (int)eup[j];
;                         const int ups = __builtin_amdgcn_update_dpp(0, g, 0x111, 0xf, 0xf, true);
;                         const int oldd = m < 3 ? shl_((int)gp[m < 3 ? m + 1 : 3][j], lane0r) : (int)edp[j];
;                         const int dns = __builtin_amdgcn_update_dpp(0, g, 0x101, 0xf, 0xf, true);
;                         UP[j] = (unsigned)(frL == 0 ? oldu : ups); DN[j] = (unsigned)(frL == 15 ? oldd : dns); GG[j] = (unsigned)g; }
;                     const f16x8 uph = __builtin_bit_cast(f16x8, UP), dnh = __builtin_bit_cast(f16x8, DN), ggh = __builtin_bit_cast(f16x8, GG);
;                     f16x2 yv[4];
;                     yv[0] = __builtin_shufflevector(uph, uph, 0, 1) * w0p[0] + __builtin_shufflevector(ggh, ggh, 0, 1) * w1p[0] + __builtin_shufflevector(dnh, dnh, 0, 1) * w2p[0] + bbp[0];
;                     yv[1] = __builtin_shufflevector(uph, uph, 2, 3) * w0p[1] + __builtin_shufflevector(ggh, ggh, 2, 3) * w1p[1] + __builtin_shufflevector(dnh, dnh, 2, 3) * w2p[1] + bbp[1];
;                     yv[2] = __builtin_shufflevector(uph, uph, 4, 5) * w0p[2] + __builtin_shufflevector(ggh, ggh, 4, 5) * w1p[2] + __builtin_shufflevector(dnh, dnh, 4, 5) * w2p[2] + bbp[2];
;                     yv[3] = __builtin_shufflevector(uph, uph, 6, 7) * w0p[3] + __builtin_shufflevector(ggh, ggh, 6, 7) * w1p[3] + __builtin_shufflevector(dnh, dnh, 6, 7) * w2p[3] + bbp[3];
;                     u32x4 o;
; #pragma unroll
;                     for (int n = 0; n < 2; ++n)
; #pragma unroll
;                         for (int q = 0; q < 2; ++q) { const int j = 2 * n + q;
;                             if (m == 0 && c == 0 && frL == 0 && pmod != 0) { const size_t off = (size_t)(u.pm * 2 + 0) * DFF + fb + 4 * n + 2 * q; *(f32x2*)(GB + off) = (f32x2){acc[ai][1][0][n][2 * q], acc[ai][1][0][n][2 * q + 1]}; *(f32x2*)(YP + off) = (f32x2){(float)yv[j][0], (float)yv[j][1]}; *(f32x2*)(VB + off) = (f32x2){acc[ai][0][0][n][2 * q], acc[ai][0][0][n][2 * q + 1]}; }
	v_cndmask_b32_e64 v169, v175, v169, s[10:11]
	s_waitcnt lgkmcnt(0)
	v_cndmask_b32_e64 v175, v177, v176, s[8:9]
	v_mov_b32_dpp v177, v138 row_ror:15 row_mask:0xf bank_mask:0xf
	v_pk_mul_f16 v172, v164, v172
	v_mov_b32_dpp v176, v140 row_shr:1 row_mask:0xf bank_mask:0xf bound_ctrl:1
	v_pk_fma_f16 v172, v156, v143, v172
	v_pk_mul_f16 v171, v166, v171
	v_pk_fma_f16 v172, v163, v173, v172
	s_waitcnt lgkmcnt(0)
	v_cndmask_b32_e64 v167, v176, v167, s[10:11]
	v_pk_mul_f16 v169, v168, v169
	v_pk_fma_f16 v171, v158, v142, v171
	v_pk_add_f16 v172, v159, v172
	v_mov_b32_dpp v178, v140 row_shl:1 row_mask:0xf bank_mask:0xf bound_ctrl:1
	v_pk_mul_f16 v167, v170, v167
	v_pk_fma_f16 v169, v160, v141, v169
	v_pk_fma_f16 v171, v161, v174, v171
	v_and_b32_e32 v174, 0x7fff7fff, v172
	s_waitcnt lgkmcnt(0)
	v_cndmask_b32_e64 v176, v178, v177, s[8:9]
	v_pk_fma_f16 v167, v162, v140, v167
	v_pk_fma_f16 v169, v152, v175, v169
	v_pk_fma_f16 v175, v174, s45, 1.0 op_sel_hi:[1,0,0]
	v_pk_fma_f16 v167, v154, v176, v167
	v_rcp_f16_e32 v176, v175
	v_rcp_f16_sdwa v175, v175 dst_sel:DWORD dst_unused:UNUSED_PAD src0_sel:WORD_1
	v_pk_mul_f16 v179, v172, v172
	v_pk_add_f16 v171, v157, v171
	v_pk_mul_f16 v179, v179, s72 op_sel_hi:[1,0]
	v_pack_b32_f16 v175, v176, v175
	v_pk_fma_f16 v176, v175, s55, v228 op_sel_hi:[1,0,0]
	v_exp_f16_e32 v183, v179
	v_exp_f16_sdwa v179, v179 dst_sel:DWORD dst_unused:UNUSED_PAD src0_sel:WORD_1
	v_pk_fma_f16 v176, v175, v176, s65 op_sel_hi:[1,1,0]
	v_pk_max_f16 v172, v172, 0
	v_pk_fma_f16 v176, v175, v176, s68 op_sel_hi:[1,1,0]
	v_pack_b32_f16 v179, v183, v179
	v_pk_fma_f16 v176, v175, v176, s69 op_sel_hi:[1,1,0]
	v_pk_mul_f16 v178, v171, v171
	v_pk_mul_f16 v175, v175, v176
	v_pk_mul_f16 v178, v178, s72 op_sel_hi:[1,0]
	v_pk_mul_f16 v175, v179, v175
	v_pk_add_f16 v169, v155, v169
	v_pk_fma_f16 v172, v174, v175, v172 neg_lo:[1,0,0] neg_hi:[1,0,0]
	v_and_b32_e32 v174, 0x7fff7fff, v171
	v_pk_fma_f16 v175, v174, s45, 1.0 op_sel_hi:[1,0,0]
	v_pk_max_f16 v171, v171, 0
	v_rcp_f16_e32 v179, v175
	v_rcp_f16_sdwa v175, v175 dst_sel:DWORD dst_unused:UNUSED_PAD src0_sel:WORD_1
	v_pk_mul_f16 v177, v169, v169
	v_cvt_pk_f16_f32 v173, v112, v113
	v_pk_mul_f16 v177, v177, s72 op_sel_hi:[1,0]
	v_pack_b32_f16 v175, v179, v175
	v_pk_fma_f16 v179, v175, s55, v228 op_sel_hi:[1,0,0]
	v_pk_mul_f16 v172, v173, v172
	v_pk_fma_f16 v179, v175, v179, s65 op_sel_hi:[1,1,0]
	v_cvt_pk_f16_f32 v173, v114, v115
	v_pk_fma_f16 v179, v175, v179, s68 op_sel_hi:[1,1,0]
	v_pk_add_f16 v167, v153, v167
	v_pk_fma_f16 v179, v175, v179, s69 op_sel_hi:[1,1,0]
	v_pk_mul_f16 v176, v167, v167
	v_pk_mul_f16 v175, v175, v179
	v_exp_f16_e32 v179, v178
	v_exp_f16_sdwa v178, v178 dst_sel:DWORD dst_unused:UNUSED_PAD src0_sel:WORD_1
	v_pk_mul_f16 v176, v176, s72 op_sel_hi:[1,0]
	v_cvt_pk_f16_f32 v145, v132, v133
	v_cvt_pk_f16_f32 v132, v72, v73
	v_pack_b32_f16 v178, v179, v178
	v_pk_mul_f16 v175, v178, v175
	v_mov_b32_dpp v143, v143 row_ror:1 row_mask:0xf bank_mask:0xf
	v_pk_fma_f16 v171, v174, v175, v171 neg_lo:[1,0,0] neg_hi:[1,0,0]
	v_and_b32_e32 v174, 0x7fff7fff, v169
	v_pk_fma_f16 v175, v174, s45, 1.0 op_sel_hi:[1,0,0]
	v_pk_mul_f16 v171, v173, v171
	v_rcp_f16_e32 v178, v175
	v_rcp_f16_sdwa v175, v175 dst_sel:DWORD dst_unused:UNUSED_PAD src0_sel:WORD_1
	v_add_u32_e32 v171, 0x40004, v171
	v_pk_max_f16 v169, v169, 0
	v_and_b32_e32 v173, 0xfff8fff8, v171
	v_pack_b32_f16 v175, v178, v175
	v_pk_fma_f16 v178, v175, s55, v228 op_sel_hi:[1,0,0]
	v_cvt_pk_f16_f32 v171, v108, v109
	v_pk_fma_f16 v178, v175, v178, s65 op_sel_hi:[1,1,0]
	v_cvt_pk_f16_f32 v133, v74, v75
	v_pk_fma_f16 v178, v175, v178, s68 op_sel_hi:[1,1,0]
	v_mov_b32_dpp v142, v142 row_ror:1 row_mask:0xf bank_mask:0xf
	v_pk_fma_f16 v178, v175, v178, s69 op_sel_hi:[1,1,0]
	v_add_u32_e32 v172, 0x40004, v172
	v_pk_mul_f16 v175, v175, v178
	v_exp_f16_e32 v178, v177
	v_exp_f16_sdwa v177, v177 dst_sel:DWORD dst_unused:UNUSED_PAD src0_sel:WORD_1
	v_and_b32_e32 v172, 0xfff8fff8, v172
	v_cvt_pk_f16_f32 v139, v134, v135
	v_cvt_pk_f16_f32 v134, v68, v69
	v_pack_b32_f16 v177, v178, v177
	v_pk_mul_f16 v175, v177, v175
	v_mov_b32_dpp v141, v141 row_ror:1 row_mask:0xf bank_mask:0xf
	v_pk_fma_f16 v169, v174, v175, v169 neg_lo:[1,0,0] neg_hi:[1,0,0]
	v_mov_b32_dpp v140, v140 row_ror:1 row_mask:0xf bank_mask:0xf
	v_pk_mul_f16 v169, v171, v169
	v_and_b32_e32 v171, 0x7fff7fff, v167
	v_pk_fma_f16 v175, v171, s45, 1.0 op_sel_hi:[1,0,0]
	v_add_u32_e32 v169, 0x40004, v169
	v_rcp_f16_e32 v177, v175
	v_rcp_f16_sdwa v175, v175 dst_sel:DWORD dst_unused:UNUSED_PAD src0_sel:WORD_1
	v_pk_max_f16 v167, v167, 0
	v_and_b32_e32 v174, 0xfff8fff8, v169
	v_cvt_pk_f16_f32 v169, v110, v111
	v_pack_b32_f16 v175, v177, v175
	v_pk_fma_f16 v177, v175, s55, v228 op_sel_hi:[1,0,0]
	v_cvt_pk_f16_f32 v135, v70, v71
	v_pk_fma_f16 v177, v175, v177, s65 op_sel_hi:[1,1,0]
	s_movk_i32 s36, 0x1600
	v_pk_fma_f16 v177, v175, v177, s68 op_sel_hi:[1,1,0]
	s_nop 0
	v_pk_fma_f16 v177, v175, v177, s69 op_sel_hi:[1,1,0]
	s_nop 0
	v_pk_mul_f16 v175, v175, v177
	v_exp_f16_e32 v177, v176
	v_exp_f16_sdwa v176, v176 dst_sel:DWORD dst_unused:UNUSED_PAD src0_sel:WORD_1
	s_nop 0
	v_pack_b32_f16 v176, v177, v176
	v_pk_mul_f16 v175, v176, v175
	s_nop 0
	v_pk_fma_f16 v167, v171, v175, v167 neg_lo:[1,0,0] neg_hi:[1,0,0]
	v_mov_b32_dpp v171, v147 row_shl:1 row_mask:0xf bank_mask:0xf bound_ctrl:1
	v_pk_mul_f16 v167, v169, v167
	v_mov_b32_dpp v169, v132 row_ror:15 row_mask:0xf bank_mask:0xf
	v_add_u32_e32 v167, 0x40004, v167
	v_and_b32_e32 v175, 0xfff8fff8, v167
	v_add_u32_e32 v167, 16, v32
	v_mad_i64_i32 v[176:177], s[12:13], v167, s29, v[150:151]
	s_nop 0
	v_mov_b32_dpp v167, v147 row_shr:1 row_mask:0xf bank_mask:0xf bound_ctrl:1
	s_waitcnt lgkmcnt(0)
;     __device__ __forceinline__ void operator()(const f32x4 (&acc)[2][2][4][2], const GUnit& u, int wr, int wc, int fr, int fq, LAS unsigned char* lds) const {
;     ...
;                     for (int j = 0; j < 4; ++j) { const int g = (int)gp[m][j];
;                         const int oldu = m > 0 ? shl_((int)gp[m > 0 ? m - 1 : 0][j], lane15) : (int)eup[j];
;                         const int ups = __builtin_amdgcn_update_dpp(0, g, 0x111, 0xf, 0xf, true);
;                         const int oldd = m < 3 ? shl_((int)gp[m < 3 ? m + 1 : 3][j], lane0r) : (int)edp[j];
;                         const int dns = __builtin_amdgcn_update_dpp(0, g, 0x101, 0xf, 0xf, true);
;                         UP[j] = (unsigned)(frL == 0 ? oldu : ups); DN[j] = (unsigned)(frL == 15 ? oldd : dns); GG[j] = (unsigned)g; }
;                     const f16x8 uph = __builtin_bit_cast(f16x8, UP), dnh = __builtin_bit_cast(f16x8, DN), ggh = __builtin_bit_cast(f16x8, GG);
;                     f16x2 yv[4];
;                     yv[0] = __builtin_shufflevector(uph, uph, 0, 1) * w0p[0] + __builtin_shufflevector(ggh, ggh, 0, 1) * w1p[0] + __builtin_shufflevector(dnh, dnh, 0, 1) * w2p[0] + bbp[0];
;                     yv[1] = __builtin_shufflevector(uph, uph, 2, 3) * w0p[1] + __builtin_shufflevector(ggh, ggh, 2, 3) * w1p[1] + __builtin_shufflevector(dnh, dnh, 2, 3) * w2p[1] + bbp[1];
;                     yv[2] = __builtin_shufflevector(uph, uph, 4, 5) * w0p[2] + __builtin_shufflevector(ggh, ggh, 4, 5) * w1p[2] + __builtin_shufflevector(dnh, dnh, 4, 5) * w2p[2] + bbp[2];
;                     yv[3] = __builtin_shufflevector(uph, uph, 6, 7) * w0p[3] + __builtin_shufflevector(ggh, ggh, 6, 7) * w1p[3] + __builtin_shufflevector(dnh, dnh, 6, 7) * w2p[3] + bbp[3];
;                     u32x4 o;
; #pragma unroll
;                     for (int n = 0; n < 2; ++n)
; #pragma unroll
;                         for (int q = 0; q < 2; ++q) { const int j = 2 * n + q;
;                             if (m == 0 && c == 0 && frL == 0 && pmod != 0) { const size_t off = (size_t)(u.pm * 2 + 0) * DFF + fb + 4 * n + 2 * q; *(f32x2*)(GB + off) = (f32x2){acc[ai][1][0][n][2 * q], acc[ai][1][0][n][2 * q + 1]}; *(f32x2*)(YP + off) = (f32x2){(float)yv[j][0], (float)yv[j][1]}; *(f32x2*)(VB + off) = (f32x2){acc[ai][0][0][n][2 * q], acc[ai][0][0][n][2 * q + 1]}; }
	v_cndmask_b32_e64 v143, v167, v143, s[10:11]
	s_waitcnt lgkmcnt(0)
	v_cndmask_b32_e64 v167, v171, v169, s[8:9]
	v_mov_b32_dpp v171, v133 row_ror:15 row_mask:0xf bank_mask:0xf
	global_store_dwordx4 v[176:177], v[172:175], off
	v_mov_b32_dpp v169, v146 row_shr:1 row_mask:0xf bank_mask:0xf bound_ctrl:1
	v_cndmask_b32_e64 v142, v169, v142, s[10:11]
	v_mov_b32_dpp v172, v146 row_shl:1 row_mask:0xf bank_mask:0xf bound_ctrl:1
	s_waitcnt lgkmcnt(0)
	v_cndmask_b32_e64 v169, v172, v171, s[8:9]
	v_mov_b32_dpp v172, v134 row_ror:15 row_mask:0xf bank_mask:0xf
	v_mov_b32_dpp v171, v144 row_shr:1 row_mask:0xf bank_mask:0xf bound_ctrl:1
	v_mov_b32_dpp v173, v144 row_shl:1 row_mask:0xf bank_mask:0xf bound_ctrl:1
	v_cndmask_b32_e64 v141, v171, v141, s[10:11]
	v_mov_b32_dpp v174, v138 row_shl:1 row_mask:0xf bank_mask:0xf bound_ctrl:1
	s_waitcnt lgkmcnt(0)
	v_cndmask_b32_e64 v171, v173, v172, s[8:9]
	v_mov_b32_dpp v173, v135 row_ror:15 row_mask:0xf bank_mask:0xf
	v_mov_b32_dpp v172, v138 row_shr:1 row_mask:0xf bank_mask:0xf bound_ctrl:1
	v_cndmask_b32_e64 v140, v172, v140, s[10:11]
	v_pk_mul_f16 v143, v164, v143
	v_pk_mul_f16 v140, v170, v140
	s_waitcnt lgkmcnt(0)
	v_cndmask_b32_e64 v172, v174, v173, s[8:9]
	v_pk_mul_f16 v142, v166, v142
	v_pk_fma_f16 v140, v162, v138, v140
	v_pk_fma_f16 v143, v156, v147, v143
	v_pk_fma_f16 v142, v158, v146, v142
	v_pk_fma_f16 v143, v163, v167, v143
	v_pk_fma_f16 v140, v154, v172, v140
	v_pk_mul_f16 v141, v168, v141
	v_pk_fma_f16 v142, v161, v169, v142
	v_pk_add_f16 v169, v153, v140
	v_pk_add_f16 v140, v159, v143
	v_pk_fma_f16 v141, v160, v144, v141
	v_and_b32_e32 v143, 0x7fff7fff, v140
	v_pk_fma_f16 v141, v152, v171, v141
	v_pk_fma_f16 v171, v143, s45, 1.0 op_sel_hi:[1,0,0]
	v_pk_mul_f16 v175, v140, v140
	v_rcp_f16_e32 v172, v171
	v_rcp_f16_sdwa v171, v171 dst_sel:DWORD dst_unused:UNUSED_PAD src0_sel:WORD_1
	v_pk_mul_f16 v175, v175, s72 op_sel_hi:[1,0]
	v_pk_add_f16 v142, v157, v142
	v_exp_f16_e32 v176, v175
	v_pack_b32_f16 v171, v172, v171
	v_pk_fma_f16 v172, v171, s55, v228 op_sel_hi:[1,0,0]
	v_exp_f16_sdwa v175, v175 dst_sel:DWORD dst_unused:UNUSED_PAD src0_sel:WORD_1
	v_pk_fma_f16 v172, v171, v172, s65 op_sel_hi:[1,1,0]
	v_pk_max_f16 v140, v140, 0
	v_pk_fma_f16 v172, v171, v172, s68 op_sel_hi:[1,1,0]
	v_pack_b32_f16 v175, v176, v175
	v_pk_fma_f16 v172, v171, v172, s69 op_sel_hi:[1,1,0]
	v_pk_mul_f16 v174, v142, v142
	v_pk_mul_f16 v171, v171, v172
	v_pk_mul_f16 v174, v174, s72 op_sel_hi:[1,0]
	v_pk_mul_f16 v171, v175, v171
	v_pk_add_f16 v167, v155, v141
	v_pk_fma_f16 v140, v143, v171, v140 neg_lo:[1,0,0] neg_hi:[1,0,0]
	v_and_b32_e32 v143, 0x7fff7fff, v142
	v_pk_fma_f16 v171, v143, s45, 1.0 op_sel_hi:[1,0,0]
	v_pk_max_f16 v142, v142, 0
	v_rcp_f16_e32 v175, v171
	v_rcp_f16_sdwa v171, v171 dst_sel:DWORD dst_unused:UNUSED_PAD src0_sel:WORD_1
	v_pk_mul_f16 v173, v167, v167
	v_pk_mul_f16 v172, v169, v169
	v_pk_mul_f16 v173, v173, s72 op_sel_hi:[1,0]
	v_pack_b32_f16 v171, v175, v171
	v_pk_fma_f16 v175, v171, s55, v228 op_sel_hi:[1,0,0]
	v_pk_mul_f16 v172, v172, s72 op_sel_hi:[1,0]
	v_pk_fma_f16 v175, v171, v175, s65 op_sel_hi:[1,1,0]
	v_cvt_pk_f16_f32 v141, v96, v97
	v_pk_fma_f16 v175, v171, v175, s68 op_sel_hi:[1,1,0]
	v_pk_mul_f16 v140, v141, v140
	v_pk_fma_f16 v175, v171, v175, s69 op_sel_hi:[1,1,0]
	v_cvt_pk_f16_f32 v141, v98, v99
	v_pk_mul_f16 v171, v171, v175
	v_exp_f16_e32 v175, v174
	v_exp_f16_sdwa v174, v174 dst_sel:DWORD dst_unused:UNUSED_PAD src0_sel:WORD_1
	v_add_u32_e32 v140, 0x40004, v140
	v_and_b32_e32 v140, 0xfff8fff8, v140
	v_mov_b32_dpp v138, v138 row_ror:1 row_mask:0xf bank_mask:0xf
	v_pack_b32_f16 v174, v175, v174
	v_pk_mul_f16 v171, v174, v171
	s_nop 0
	v_pk_fma_f16 v142, v143, v171, v142 neg_lo:[1,0,0] neg_hi:[1,0,0]
	v_and_b32_e32 v143, 0x7fff7fff, v167
	v_pk_fma_f16 v171, v143, s45, 1.0 op_sel_hi:[1,0,0]
	v_pk_max_f16 v167, v167, 0
	v_rcp_f16_e32 v174, v171
	v_rcp_f16_sdwa v171, v171 dst_sel:DWORD dst_unused:UNUSED_PAD src0_sel:WORD_1
	v_pk_mul_f16 v141, v141, v142
	v_cvt_pk_f16_f32 v142, v92, v93
	v_add_u32_e32 v141, 0x40004, v141
	v_pack_b32_f16 v171, v174, v171
	v_pk_fma_f16 v174, v171, s55, v228 op_sel_hi:[1,0,0]
	v_and_b32_e32 v141, 0xfff8fff8, v141
	v_pk_fma_f16 v174, v171, v174, s65 op_sel_hi:[1,1,0]
	s_nop 0
	v_pk_fma_f16 v174, v171, v174, s68 op_sel_hi:[1,1,0]
	s_nop 0
	v_pk_fma_f16 v174, v171, v174, s69 op_sel_hi:[1,1,0]
	s_nop 0
	v_pk_mul_f16 v171, v171, v174
	v_exp_f16_e32 v174, v173
	v_exp_f16_sdwa v173, v173 dst_sel:DWORD dst_unused:UNUSED_PAD src0_sel:WORD_1
	s_nop 0
	v_pack_b32_f16 v173, v174, v173
	v_pk_mul_f16 v171, v173, v171
	s_nop 0
	v_pk_fma_f16 v143, v143, v171, v167 neg_lo:[1,0,0] neg_hi:[1,0,0]
	v_and_b32_e32 v167, 0x7fff7fff, v169
	v_pk_fma_f16 v171, v167, s45, 1.0 op_sel_hi:[1,0,0]
	v_pk_max_f16 v169, v169, 0
	v_rcp_f16_e32 v173, v171
	v_rcp_f16_sdwa v171, v171 dst_sel:DWORD dst_unused:UNUSED_PAD src0_sel:WORD_1
	v_pk_mul_f16 v142, v142, v143
	v_cvt_pk_f16_f32 v143, v94, v95
	v_add_u32_e32 v142, 0x40004, v142
	v_pack_b32_f16 v171, v173, v171
	v_pk_fma_f16 v173, v171, s55, v228 op_sel_hi:[1,0,0]
	v_and_b32_e32 v142, 0xfff8fff8, v142
	v_pk_fma_f16 v173, v171, v173, s65 op_sel_hi:[1,1,0]
	s_nop 0
	v_pk_fma_f16 v173, v171, v173, s68 op_sel_hi:[1,1,0]
	s_nop 0
	v_pk_fma_f16 v173, v171, v173, s69 op_sel_hi:[1,1,0]
	s_nop 0
	v_pk_mul_f16 v171, v171, v173
	v_exp_f16_e32 v173, v172
	v_exp_f16_sdwa v172, v172 dst_sel:DWORD dst_unused:UNUSED_PAD src0_sel:WORD_1
	s_nop 0
	v_pack_b32_f16 v172, v173, v172
	v_pk_mul_f16 v171, v172, v171
	s_nop 0
	v_pk_fma_f16 v167, v167, v171, v169 neg_lo:[1,0,0] neg_hi:[1,0,0]
	s_nop 0
	v_pk_mul_f16 v143, v143, v167
	v_add_u32_e32 v167, 32, v32
	v_add_u32_e32 v143, 0x40004, v143
	v_and_b32_e32 v143, 0xfff8fff8, v143
	v_mad_i64_i32 v[172:173], s[12:13], v167, s29, v[150:151]
	global_store_dwordx4 v[172:173], v[140:143], off
	s_nop 1
	v_mov_b32_dpp v140, v147 row_ror:1 row_mask:0xf bank_mask:0xf
	v_readlane_b32 s12, v251, 57
	v_mov_b32_dpp v141, v132 row_shr:1 row_mask:0xf bank_mask:0xf bound_ctrl:1
	v_mov_b32_dpp v142, v132 row_shl:1 row_mask:0xf bank_mask:0xf bound_ctrl:1
	v_mov_b32_dpp v143, v133 row_shr:1 row_mask:0xf bank_mask:0xf bound_ctrl:1
	s_waitcnt lgkmcnt(0)
;     __device__ __forceinline__ void operator()(const f32x4 (&acc)[2][2][4][2], const GUnit& u, int wr, int wc, int fr, int fq, LAS unsigned char* lds) const {
;     ...
;                     for (int j = 0; j < 4; ++j) { const int g = (int)gp[m][j];
;                         const int oldu = m > 0 ? shl_((int)gp[m > 0 ? m - 1 : 0][j], lane15) : (int)eup[j];
;                         const int ups = __builtin_amdgcn_update_dpp(0, g, 0x111, 0xf, 0xf, true);
;                         const int oldd = m < 3 ? shl_((int)gp[m < 3 ? m + 1 : 3][j], lane0r) : (int)edp[j];
;                         const int dns = __builtin_amdgcn_update_dpp(0, g, 0x101, 0xf, 0xf, true);
;                         UP[j] = (unsigned)(frL == 0 ? oldu : ups); DN[j] = (unsigned)(frL == 15 ? oldd : dns); GG[j] = (unsigned)g; }
;                     const f16x8 uph = __builtin_bit_cast(f16x8, UP), dnh = __builtin_bit_cast(f16x8, DN), ggh = __builtin_bit_cast(f16x8, GG);
;                     f16x2 yv[4];
;                     yv[0] = __builtin_shufflevector(uph, uph, 0, 1) * w0p[0] + __builtin_shufflevector(ggh, ggh, 0, 1) * w1p[0] + __builtin_shufflevector(dnh, dnh, 0, 1) * w2p[0] + bbp[0];
;                     yv[1] = __builtin_shufflevector(uph, uph, 2, 3) * w0p[1] + __builtin_shufflevector(ggh, ggh, 2, 3) * w1p[1] + __builtin_shufflevector(dnh, dnh, 2, 3) * w2p[1] + bbp[1];
;                     yv[2] = __builtin_shufflevector(uph, uph, 4, 5) * w0p[2] + __builtin_shufflevector(ggh, ggh, 4, 5) * w1p[2] + __builtin_shufflevector(dnh, dnh, 4, 5) * w2p[2] + bbp[2];
;                     yv[3] = __builtin_shufflevector(uph, uph, 6, 7) * w0p[3] + __builtin_shufflevector(ggh, ggh, 6, 7) * w1p[3] + __builtin_shufflevector(dnh, dnh, 6, 7) * w2p[3] + bbp[3];
;                     u32x4 o;
; #pragma unroll
;                     for (int n = 0; n < 2; ++n)
; #pragma unroll
;                         for (int q = 0; q < 2; ++q) { const int j = 2 * n + q;
;                             if (m == 0 && c == 0 && frL == 0 && pmod != 0) { const size_t off = (size_t)(u.pm * 2 + 0) * DFF + fb + 4 * n + 2 * q; *(f32x2*)(GB + off) = (f32x2){acc[ai][1][0][n][2 * q], acc[ai][1][0][n][2 * q + 1]}; *(f32x2*)(YP + off) = (f32x2){(float)yv[j][0], (float)yv[j][1]}; *(f32x2*)(VB + off) = (f32x2){acc[ai][0][0][n][2 * q], acc[ai][0][0][n][2 * q + 1]}; }
	v_cndmask_b32_e64 v140, v141, v140, s[10:11]
	v_cndmask_b32_e64 v141, v142, v145, s[8:9]
	v_mov_b32_dpp v142, v146 row_ror:1 row_mask:0xf bank_mask:0xf
	v_mov_b32_dpp v145, v133 row_shl:1 row_mask:0xf bank_mask:0xf bound_ctrl:1
	v_cndmask_b32_e64 v139, v145, v139, s[8:9]
	v_pk_mul_f16 v140, v164, v140
	v_mov_b32_dpp v145, v134 row_shl:1 row_mask:0xf bank_mask:0xf bound_ctrl:1
	s_waitcnt lgkmcnt(0)
	v_cndmask_b32_e64 v142, v143, v142, s[10:11]
	v_mov_b32_dpp v143, v144 row_ror:1 row_mask:0xf bank_mask:0xf
	v_mov_b32_dpp v144, v134 row_shr:1 row_mask:0xf bank_mask:0xf bound_ctrl:1
	v_cndmask_b32_e64 v137, v145, v137, s[8:9]
	v_mov_b32_dpp v145, v135 row_shl:1 row_mask:0xf bank_mask:0xf bound_ctrl:1
	v_pk_mul_f16 v142, v166, v142
	s_waitcnt lgkmcnt(0)
	v_cndmask_b32_e64 v143, v144, v143, s[10:11]
	v_mov_b32_dpp v144, v135 row_shr:1 row_mask:0xf bank_mask:0xf bound_ctrl:1
	v_cndmask_b32_e64 v138, v144, v138, s[10:11]
	v_pk_mul_f16 v143, v168, v143
	v_pk_mul_f16 v138, v170, v138
	v_readlane_b32 s13, v251, 58
	v_cndmask_b32_e64 v136, v145, v136, s[8:9]
	v_pk_fma_f16 v135, v162, v135, v138
	v_pk_fma_f16 v134, v160, v134, v143
	v_pk_fma_f16 v133, v158, v133, v142
	v_pk_fma_f16 v132, v156, v132, v140
	s_and_b64 s[12:13], s[12:13], s[8:9]
	v_pk_fma_f16 v138, v163, v141, v132
	v_pk_fma_f16 v139, v161, v139, v133
	v_pk_fma_f16 v133, v152, v137, v134
	v_pk_fma_f16 v132, v154, v136, v135
	s_and_b64 s[12:13], s[12:13], s[80:81]
	v_pk_add_f16 v132, v153, v132
	v_pk_add_f16 v133, v155, v133
	v_pk_add_f16 v134, v157, v139
	v_pk_add_f16 v135, v159, v138
	s_xor_b64 s[12:13], s[12:13], -1
	s_and_saveexec_b64 s[68:69], s[12:13]
	s_xor_b64 s[72:73], exec, s[68:69]
	s_andn2_saveexec_b64 s[72:73], s[72:73]
	s_cbranch_execz .LBB0_274
	s_lshl_b32 s29, s37, 1
	s_or_b32 s29, s29, 1
	v_mov_b32_e32 v136, 0xb00
	v_mad_i64_i32 v[136:137], s[68:69], s29, v136, v[190:191]
	v_readlane_b32 s68, v251, 22
	v_lshlrev_b64 v[136:137], 2, v[136:137]
	v_readlane_b32 s69, v251, 23
	v_cvt_f32_f16_sdwa v139, v135 dst_sel:DWORD dst_unused:UNUSED_PAD src0_sel:WORD_1
	v_cvt_f32_f16_e32 v138, v135
	v_lshl_add_u64 v[140:141], s[68:69], 0, v[136:137]
	v_readlane_b32 s68, v251, 24
	v_readlane_b32 s69, v251, 25
	global_store_dwordx2 v[140:141], v[72:73], off
	s_nop 0
	v_lshl_add_u64 v[140:141], s[68:69], 0, v[136:137]
	v_readlane_b32 s68, v251, 26
	v_readlane_b32 s69, v251, 27
	global_store_dwordx2 v[140:141], v[138:139], off
	s_nop 0
	v_lshl_add_u64 v[136:137], s[68:69], 0, v[136:137]
	global_store_dwordx2 v[136:137], v[80:81], off

;     __device__ __forceinline__ void operator()(const f32x4 (&acc)[2][2][4][2], const GUnit& u, int wr, int wc, int fr, int fq, LAS unsigned char* lds) const {
;     ...
;                     for (int j = 0; j < 4; ++j) { const int g = (int)gp[m][j];
;                         const int oldu = m > 0 ? shl_((int)gp[m > 0 ? m - 1 : 0][j], lane15) : (int)eup[j];
;                         const int ups = __builtin_amdgcn_update_dpp(0, g, 0x111, 0xf, 0xf, true);
;                         const int oldd = m < 3 ? shl_((int)gp[m < 3 ? m + 1 : 3][j], lane0r) : (int)edp[j];
;                         const int dns = __builtin_amdgcn_update_dpp(0, g, 0x101, 0xf, 0xf, true);
;                         UP[j] = (unsigned)(frL == 0 ? oldu : ups); DN[j] = (unsigned)(frL == 15 ? oldd : dns); GG[j] = (unsigned)g; }
;                     const f16x8 uph = __builtin_bit_cast(f16x8, UP), dnh = __builtin_bit_cast(f16x8, DN), ggh = __builtin_bit_cast(f16x8, GG);
;                     f16x2 yv[4];
;                     yv[0] = __builtin_shufflevector(uph, uph, 0, 1) * w0p[0] + __builtin_shufflevector(ggh, ggh, 0, 1) * w1p[0] + __builtin_shufflevector(dnh, dnh, 0, 1) * w2p[0] + bbp[0];
;                     yv[1] = __builtin_shufflevector(uph, uph, 2, 3) * w0p[1] + __builtin_shufflevector(ggh, ggh, 2, 3) * w1p[1] + __builtin_shufflevector(dnh, dnh, 2, 3) * w2p[1] + bbp[1];
;                     yv[2] = __builtin_shufflevector(uph, uph, 4, 5) * w0p[2] + __builtin_shufflevector(ggh, ggh, 4, 5) * w1p[2] + __builtin_shufflevector(dnh, dnh, 4, 5) * w2p[2] + bbp[2];
;                     yv[3] = __builtin_shufflevector(uph, uph, 6, 7) * w0p[3] + __builtin_shufflevector(ggh, ggh, 6, 7) * w1p[3] + __builtin_shufflevector(dnh, dnh, 6, 7) * w2p[3] + bbp[3];
;                     u32x4 o;
; #pragma unroll
;                     for (int n = 0; n < 2; ++n)
; #pragma unroll
;                         for (int q = 0; q < 2; ++q) { const int j = 2 * n + q;
;                             if (m == 0 && c == 0 && frL == 0 && pmod != 0) { const size_t off = (size_t)(u.pm * 2 + 0) * DFF + fb + 4 * n + 2 * q; *(f32x2*)(GB + off) = (f32x2){acc[ai][1][0][n][2 * q], acc[ai][1][0][n][2 * q + 1]}; *(f32x2*)(YP + off) = (f32x2){(float)yv[j][0], (float)yv[j][1]}; *(f32x2*)(VB + off) = (f32x2){acc[ai][0][0][n][2 * q], acc[ai][0][0][n][2 * q + 1]}; }
.LBB0_284:
	v_cvt_pk_f16_f32 v178, v40, v41
	s_waitcnt lgkmcnt(0)
	v_cvt_pk_f16_f32 v133, v132, v133
	v_cvt_pk_f16_f32 v132, v134, v135
	v_mov_b32_dpp v135, v178 row_ror:15 row_mask:0xf bank_mask:0xf
	v_cvt_pk_f16_f32 v174, v56, v57
	v_cvt_pk_f16_f32 v172, v136, v137
	v_cvt_pk_f16_f32 v179, v42, v43
	v_cvt_pk_f16_f32 v144, v144, v145
	v_cvt_pk_f16_f32 v145, v146, v147
	v_mov_b32_dpp v146, v174 row_shr:1 row_mask:0xf bank_mask:0xf bound_ctrl:1
	v_cndmask_b32_e64 v146, v146, v172, s[10:11]
	v_mov_b32_dpp v172, v179 row_ror:15 row_mask:0xf bank_mask:0xf
	v_cvt_pk_f16_f32 v175, v58, v59
	v_mov_b32_dpp v147, v174 row_shl:1 row_mask:0xf bank_mask:0xf bound_ctrl:1
	v_cvt_pk_f16_f32 v173, v138, v139
	v_cvt_pk_f16_f32 v181, v36, v37
	s_waitcnt lgkmcnt(0)
	v_cndmask_b32_e64 v135, v147, v135, s[8:9]
	v_mov_b32_dpp v147, v175 row_shr:1 row_mask:0xf bank_mask:0xf bound_ctrl:1
	v_cndmask_b32_e64 v147, v147, v173, s[10:11]
	v_mov_b32_dpp v173, v181 row_ror:15 row_mask:0xf bank_mask:0xf
	v_pk_mul_f16 v146, v164, v146
	v_cvt_pk_f16_f32 v176, v52, v53
	v_mov_b32_dpp v189, v175 row_shl:1 row_mask:0xf bank_mask:0xf bound_ctrl:1
	v_pk_fma_f16 v146, v156, v174, v146
	v_cvt_pk_f16_f32 v183, v38, v39
	s_waitcnt lgkmcnt(0)
	v_cndmask_b32_e64 v172, v189, v172, s[8:9]
	v_mov_b32_dpp v189, v176 row_shr:1 row_mask:0xf bank_mask:0xf bound_ctrl:1
	v_pk_mul_f16 v147, v166, v147
	v_pk_fma_f16 v135, v163, v135, v146
	v_cndmask_b32_e64 v144, v189, v144, s[10:11]
	v_mov_b32_dpp v189, v183 row_ror:15 row_mask:0xf bank_mask:0xf
	v_pk_fma_f16 v147, v158, v175, v147
	v_pk_add_f16 v135, v159, v135
	v_cvt_pk_f16_f32 v177, v54, v55
	v_mov_b32_dpp v192, v176 row_shl:1 row_mask:0xf bank_mask:0xf bound_ctrl:1
	v_pk_mul_f16 v144, v168, v144
	v_pk_fma_f16 v146, v161, v172, v147
	v_and_b32_e32 v147, 0x7fff7fff, v135
	s_movk_i32 s36, 0x336a
	s_waitcnt lgkmcnt(0)
	v_cndmask_b32_e64 v173, v192, v173, s[8:9]
	v_mov_b32_dpp v192, v177 row_shr:1 row_mask:0xf bank_mask:0xf bound_ctrl:1
	v_pk_fma_f16 v144, v160, v176, v144
	v_pk_fma_f16 v172, v147, s36, 1.0 op_sel_hi:[1,0,0]
	v_cndmask_b32_e64 v145, v192, v145, s[10:11]
	v_pk_fma_f16 v144, v152, v173, v144
	v_rcp_f16_e32 v173, v172
	v_rcp_f16_sdwa v172, v172 dst_sel:DWORD dst_unused:UNUSED_PAD src0_sel:WORD_1
	v_mov_b32_dpp v193, v177 row_shl:1 row_mask:0xf bank_mask:0xf bound_ctrl:1
	v_pk_mul_f16 v145, v170, v145
	s_waitcnt lgkmcnt(0)
	v_cndmask_b32_e64 v189, v193, v189, s[8:9]
	v_pk_fma_f16 v145, v162, v177, v145
	s_movk_i32 s45, 0x383f
	v_pk_fma_f16 v145, v154, v189, v145
	s_movk_i32 s55, 0x39b0
	v_pk_add_f16 v192, v153, v145
	v_pack_b32_f16 v145, v173, v172
	v_pk_fma_f16 v172, v145, s45, v228 op_sel_hi:[1,0,0]
	s_mov_b32 s65, 0xb08d
	v_pk_fma_f16 v172, v145, v172, s55 op_sel_hi:[1,1,0]
	s_movk_i32 s68, 0x3014
	v_pk_fma_f16 v172, v145, v172, s65 op_sel_hi:[1,1,0]
	s_mov_b32 s69, 0xb9c5
	v_pk_fma_f16 v172, v145, v172, s68 op_sel_hi:[1,1,0]
	v_pk_add_f16 v146, v157, v146
	v_pk_mul_f16 v145, v145, v172
	v_pk_mul_f16 v172, v135, v135
	v_pk_max_f16 v135, v135, 0
	v_pk_mul_f16 v172, v172, s69 op_sel_hi:[1,0]
	v_pk_add_f16 v189, v155, v144
	v_exp_f16_e32 v173, v172
	v_exp_f16_sdwa v172, v172 dst_sel:DWORD dst_unused:UNUSED_PAD src0_sel:WORD_1
	v_cvt_pk_f16_f32 v144, v64, v65
	v_pk_mul_f16 v195, v146, v146
	v_pk_mul_f16 v194, v189, v189
	v_pack_b32_f16 v172, v173, v172
	v_pk_mul_f16 v145, v172, v145
	v_pk_mul_f16 v173, v195, s69 op_sel_hi:[1,0]
	v_pk_fma_f16 v135, v147, v145, v135 neg_lo:[1,0,0] neg_hi:[1,0,0]
	v_and_b32_e32 v145, 0x7fff7fff, v146
	v_pk_mul_f16 v135, v144, v135
	v_pk_fma_f16 v144, v145, s36, 1.0 op_sel_hi:[1,0,0]
	v_exp_f16_e32 v195, v173
	v_rcp_f16_e32 v147, v144
	v_rcp_f16_sdwa v172, v144 dst_sel:DWORD dst_unused:UNUSED_PAD src0_sel:WORD_1
	v_exp_f16_sdwa v173, v173 dst_sel:DWORD dst_unused:UNUSED_PAD src0_sel:WORD_1
	v_add_u32_e32 v135, 0x40004, v135
	v_pk_max_f16 v146, v146, 0
	v_pack_b32_f16 v147, v147, v172
	v_pk_fma_f16 v172, v147, s45, v228 op_sel_hi:[1,0,0]
	v_and_b32_e32 v144, 0xfff8fff8, v135
	v_pk_fma_f16 v172, v147, v172, s55 op_sel_hi:[1,1,0]
	v_cvt_pk_f16_f32 v135, v66, v67
	v_pk_fma_f16 v172, v147, v172, s65 op_sel_hi:[1,1,0]
	v_pk_mul_f16 v193, v192, v192
	v_pk_fma_f16 v172, v147, v172, s68 op_sel_hi:[1,1,0]
	v_add_u32_e32 v134, 0x80, v32
	v_pk_mul_f16 v147, v147, v172
	v_pack_b32_f16 v172, v195, v173
	v_pk_mul_f16 v147, v172, v147
	v_pk_mul_f16 v173, v194, s69 op_sel_hi:[1,0]
	v_pk_fma_f16 v145, v145, v147, v146 neg_lo:[1,0,0] neg_hi:[1,0,0]
	v_and_b32_e32 v146, 0x7fff7fff, v189
	v_pk_mul_f16 v135, v135, v145
	v_pk_fma_f16 v145, v146, s36, 1.0 op_sel_hi:[1,0,0]
	v_exp_f16_e32 v194, v173
	v_rcp_f16_e32 v147, v145
	v_rcp_f16_sdwa v172, v145 dst_sel:DWORD dst_unused:UNUSED_PAD src0_sel:WORD_1
	v_exp_f16_sdwa v173, v173 dst_sel:DWORD dst_unused:UNUSED_PAD src0_sel:WORD_1
	v_add_u32_e32 v135, 0x40004, v135
	v_and_b32_e32 v145, 0xfff8fff8, v135
	v_pack_b32_f16 v147, v147, v172
	v_pk_fma_f16 v172, v147, s45, v228 op_sel_hi:[1,0,0]
	v_cvt_pk_f16_f32 v135, v60, v61
	v_pk_fma_f16 v172, v147, v172, s55 op_sel_hi:[1,1,0]
	s_movk_i32 s29, 0x1600
	v_pk_fma_f16 v172, v147, v172, s65 op_sel_hi:[1,1,0]
	v_cvt_pk_f16_f32 v171, v20, v21
	v_pk_fma_f16 v172, v147, v172, s68 op_sel_hi:[1,1,0]
	v_or_b32_e32 v167, 60, v165
	v_pk_mul_f16 v147, v147, v172
	v_pack_b32_f16 v172, v194, v173
	v_pk_max_f16 v173, v189, 0
	v_pk_mul_f16 v147, v172, v147
	v_pk_mul_f16 v189, v193, s69 op_sel_hi:[1,0]
	v_pk_fma_f16 v146, v146, v147, v173 neg_lo:[1,0,0] neg_hi:[1,0,0]
	v_and_b32_e32 v147, 0x7fff7fff, v192
	v_pk_mul_f16 v135, v135, v146
	v_pk_fma_f16 v146, v147, s36, 1.0 op_sel_hi:[1,0,0]
	v_exp_f16_e32 v193, v189
	v_rcp_f16_e32 v172, v146
;     __device__ __forceinline__ void operator()(const f32x4 (&acc)[2][2][4][2], const GUnit& u, int wr, int wc, int fr, int fq, LAS unsigned char* lds) const {
;     ...
;                     for (int j = 0; j < 4; ++j) { const int g = (int)gp[m][j];
;                         const int oldu = m > 0 ? shl_((int)gp[m > 0 ? m - 1 : 0][j], lane15) : (int)eup[j];
;                         const int ups = __builtin_amdgcn_update_dpp(0, g, 0x111, 0xf, 0xf, true);
;                         const int oldd = m < 3 ? shl_((int)gp[m < 3 ? m + 1 : 3][j], lane0r) : (int)edp[j];
;                         const int dns = __builtin_amdgcn_update_dpp(0, g, 0x101, 0xf, 0xf, true);
;                         UP[j] = (unsigned)(frL == 0 ? oldu : ups); DN[j] = (unsigned)(frL == 15 ? oldd : dns); GG[j] = (unsigned)g; }
;                     const f16x8 uph = __builtin_bit_cast(f16x8, UP), dnh = __builtin_bit_cast(f16x8, DN), ggh = __builtin_bit_cast(f16x8, GG);
;                     f16x2 yv[4];
;                     yv[0] = __builtin_shufflevector(uph, uph, 0, 1) * w0p[0] + __builtin_shufflevector(ggh, ggh, 0, 1) * w1p[0] + __builtin_shufflevector(dnh, dnh, 0, 1) * w2p[0] + bbp[0];
;                     yv[1] = __builtin_shufflevector(uph, uph, 2, 3) * w0p[1] + __builtin_shufflevector(ggh, ggh, 2, 3) * w1p[1] + __builtin_shufflevector(dnh, dnh, 2, 3) * w2p[1] + bbp[1];
;                     yv[2] = __builtin_shufflevector(uph, uph, 4, 5) * w0p[2] + __builtin_shufflevector(ggh, ggh, 4, 5) * w1p[2] + __builtin_shufflevector(dnh, dnh, 4, 5) * w2p[2] + bbp[2];
;                     yv[3] = __builtin_shufflevector(uph, uph, 6, 7) * w0p[3] + __builtin_shufflevector(ggh, ggh, 6, 7) * w1p[3] + __builtin_shufflevector(dnh, dnh, 6, 7) * w2p[3] + bbp[3];
;                     u32x4 o;
; #pragma unroll
;                     for (int n = 0; n < 2; ++n)
; #pragma unroll
;                         for (int q = 0; q < 2; ++q) { const int j = 2 * n + q;
;                             if (m == 0 && c == 0 && frL == 0 && pmod != 0) { const size_t off = (size_t)(u.pm * 2 + 0) * DFF + fb + 4 * n + 2 * q; *(f32x2*)(GB + off) = (f32x2){acc[ai][1][0][n][2 * q], acc[ai][1][0][n][2 * q + 1]}; *(f32x2*)(YP + off) = (f32x2){(float)yv[j][0], (float)yv[j][1]}; *(f32x2*)(VB + off) = (f32x2){acc[ai][0][0][n][2 * q], acc[ai][0][0][n][2 * q + 1]}; }
	v_rcp_f16_sdwa v173, v146 dst_sel:DWORD dst_unused:UNUSED_PAD src0_sel:WORD_1
	v_exp_f16_sdwa v189, v189 dst_sel:DWORD dst_unused:UNUSED_PAD src0_sel:WORD_1
	v_add_u32_e32 v135, 0x40004, v135
	v_and_b32_e32 v146, 0xfff8fff8, v135
	v_pack_b32_f16 v172, v172, v173
	v_pk_fma_f16 v173, v172, s45, v228 op_sel_hi:[1,0,0]
	v_cvt_pk_f16_f32 v135, v62, v63
	v_pk_fma_f16 v173, v172, v173, s55 op_sel_hi:[1,1,0]
	v_cvt_pk_f16_f32 v169, v22, v23
	v_pk_fma_f16 v173, v172, v173, s65 op_sel_hi:[1,1,0]
	v_cvt_pk_f16_f32 v139, v142, v143
	v_pk_fma_f16 v173, v172, v173, s68 op_sel_hi:[1,1,0]
	v_cvt_pk_f16_f32 v143, v16, v17
	v_pk_mul_f16 v172, v172, v173
	v_pack_b32_f16 v173, v193, v189
	v_pk_max_f16 v189, v192, 0
	v_pk_mul_f16 v172, v173, v172
	v_cvt_pk_f16_f32 v142, v18, v19
	v_pk_fma_f16 v147, v147, v172, v189 neg_lo:[1,0,0] neg_hi:[1,0,0]
	v_mov_b32_dpp v172, v174 row_ror:1 row_mask:0xf bank_mask:0xf
	v_pk_mul_f16 v135, v135, v147
	v_mov_b32_dpp v174, v142 row_ror:15 row_mask:0xf bank_mask:0xf
	v_add_u32_e32 v135, 0x40004, v135
	v_and_b32_e32 v147, 0xfff8fff8, v135
	v_mad_i64_i32 v[134:135], s[12:13], v134, s29, v[150:151]
	global_store_dwordx4 v[134:135], v[144:147], off
	s_nop 1
	v_mov_b32_dpp v134, v171 row_ror:15 row_mask:0xf bank_mask:0xf
	v_mov_b32_dpp v145, v175 row_ror:1 row_mask:0xf bank_mask:0xf
	v_mov_b32_dpp v144, v178 row_shl:1 row_mask:0xf bank_mask:0xf bound_ctrl:1
	v_mov_b32_dpp v146, v179 row_shr:1 row_mask:0xf bank_mask:0xf bound_ctrl:1
	v_mov_b32_dpp v135, v178 row_shr:1 row_mask:0xf bank_mask:0xf bound_ctrl:1
	s_waitcnt lgkmcnt(0)
	v_cndmask_b32_e64 v134, v144, v134, s[8:9]
	v_mov_b32_dpp v144, v169 row_ror:15 row_mask:0xf bank_mask:0xf
	s_waitcnt lgkmcnt(0)
	v_cndmask_b32_e64 v145, v146, v145, s[10:11]
	v_mov_b32_dpp v146, v176 row_ror:1 row_mask:0xf bank_mask:0xf
	v_mov_b32_dpp v147, v179 row_shl:1 row_mask:0xf bank_mask:0xf bound_ctrl:1
	v_cndmask_b32_e64 v135, v135, v172, s[10:11]
	s_waitcnt lgkmcnt(0)
	v_cndmask_b32_e64 v144, v147, v144, s[8:9]
	v_mov_b32_dpp v147, v181 row_shr:1 row_mask:0xf bank_mask:0xf bound_ctrl:1
	v_mov_b32_dpp v172, v143 row_ror:15 row_mask:0xf bank_mask:0xf
	s_waitcnt lgkmcnt(0)
	v_cndmask_b32_e64 v146, v147, v146, s[10:11]
	v_mov_b32_dpp v147, v177 row_ror:1 row_mask:0xf bank_mask:0xf
	v_mov_b32_dpp v173, v181 row_shl:1 row_mask:0xf bank_mask:0xf bound_ctrl:1
	v_pk_mul_f16 v135, v164, v135
	s_waitcnt lgkmcnt(0)
	v_cndmask_b32_e64 v172, v173, v172, s[8:9]
	v_mov_b32_dpp v173, v183 row_shr:1 row_mask:0xf bank_mask:0xf bound_ctrl:1
	v_pk_mul_f16 v145, v166, v145
	v_pk_fma_f16 v135, v156, v178, v135
	s_waitcnt lgkmcnt(0)
	v_cndmask_b32_e64 v147, v173, v147, s[10:11]
	v_pk_fma_f16 v145, v158, v179, v145
	v_pk_fma_f16 v134, v163, v134, v135
	v_mov_b32_dpp v175, v183 row_shl:1 row_mask:0xf bank_mask:0xf bound_ctrl:1
	v_pk_mul_f16 v147, v170, v147
	v_pk_fma_f16 v144, v161, v144, v145
	v_pk_add_f16 v134, v159, v134
	v_cndmask_b32_e64 v173, v175, v174, s[8:9]
	v_pk_mul_f16 v146, v168, v146
	v_pk_fma_f16 v147, v162, v183, v147
	v_pk_add_f16 v145, v157, v144
	v_and_b32_e32 v144, 0x7fff7fff, v134
	v_pk_fma_f16 v146, v160, v181, v146
	v_pk_fma_f16 v135, v154, v173, v147
	v_pk_fma_f16 v147, v144, s36, 1.0 op_sel_hi:[1,0,0]
	v_pk_fma_f16 v146, v152, v172, v146
	v_rcp_f16_e32 v172, v147
	v_rcp_f16_sdwa v147, v147 dst_sel:DWORD dst_unused:UNUSED_PAD src0_sel:WORD_1
	v_cvt_pk_f16_f32 v173, v48, v49
	v_pk_mul_f16 v177, v145, v145
	v_pk_add_f16 v146, v155, v146
	v_pack_b32_f16 v147, v172, v147
	v_pk_fma_f16 v172, v147, s45, v228 op_sel_hi:[1,0,0]
	v_pk_mul_f16 v176, v146, v146
	v_pk_fma_f16 v172, v147, v172, s55 op_sel_hi:[1,1,0]
	v_pk_add_f16 v135, v153, v135
	v_pk_fma_f16 v172, v147, v172, s65 op_sel_hi:[1,1,0]
	v_pk_mul_f16 v175, v135, v135
	v_pk_fma_f16 v172, v147, v172, s68 op_sel_hi:[1,1,0]
	v_cvt_pk_f16_f32 v136, v4, v5
	v_pk_mul_f16 v147, v147, v172
	v_pk_mul_f16 v172, v134, v134
	v_pk_max_f16 v134, v134, 0
	v_pk_mul_f16 v172, v172, s69 op_sel_hi:[1,0]
	v_cvt_pk_f16_f32 v137, v6, v7
	v_exp_f16_e32 v174, v172
	v_exp_f16_sdwa v172, v172 dst_sel:DWORD dst_unused:UNUSED_PAD src0_sel:WORD_1
	v_cvt_pk_f16_f32 v138, v0, v1
	v_cvt_pk_f16_f32 v141, v140, v141
	v_cvt_pk_f16_f32 v140, v2, v3
	v_pack_b32_f16 v172, v174, v172
	v_pk_mul_f16 v147, v172, v147
	v_pk_mul_f16 v174, v177, s69 op_sel_hi:[1,0]
	v_pk_fma_f16 v134, v144, v147, v134 neg_lo:[1,0,0] neg_hi:[1,0,0]
	v_and_b32_e32 v147, 0x7fff7fff, v145
	v_pk_fma_f16 v144, v147, s36, 1.0 op_sel_hi:[1,0,0]
	v_pk_mul_f16 v134, v173, v134
	v_rcp_f16_e32 v172, v144
	v_rcp_f16_sdwa v173, v144 dst_sel:DWORD dst_unused:UNUSED_PAD src0_sel:WORD_1
	v_exp_f16_e32 v177, v174
	v_exp_f16_sdwa v174, v174 dst_sel:DWORD dst_unused:UNUSED_PAD src0_sel:WORD_1
	v_add_u32_e32 v134, 0x40004, v134
	v_pack_b32_f16 v172, v172, v173
	v_pk_fma_f16 v173, v172, s45, v228 op_sel_hi:[1,0,0]
	v_pk_max_f16 v145, v145, 0
	v_pk_fma_f16 v173, v172, v173, s55 op_sel_hi:[1,1,0]
	v_and_b32_e32 v144, 0xfff8fff8, v134
	v_pk_fma_f16 v173, v172, v173, s65 op_sel_hi:[1,1,0]
	v_cvt_pk_f16_f32 v134, v50, v51
	v_pk_fma_f16 v173, v172, v173, s68 op_sel_hi:[1,1,0]
	s_nop 0
	v_pk_mul_f16 v172, v172, v173
	v_pack_b32_f16 v173, v177, v174
	v_pk_mul_f16 v172, v173, v172
	v_pk_mul_f16 v174, v176, s69 op_sel_hi:[1,0]
	v_pk_fma_f16 v145, v147, v172, v145 neg_lo:[1,0,0] neg_hi:[1,0,0]
	v_and_b32_e32 v147, 0x7fff7fff, v146
	v_pk_mul_f16 v134, v134, v145
	v_pk_fma_f16 v145, v147, s36, 1.0 op_sel_hi:[1,0,0]
	v_exp_f16_e32 v176, v174
	v_rcp_f16_e32 v172, v145
	v_rcp_f16_sdwa v173, v145 dst_sel:DWORD dst_unused:UNUSED_PAD src0_sel:WORD_1
	v_exp_f16_sdwa v174, v174 dst_sel:DWORD dst_unused:UNUSED_PAD src0_sel:WORD_1
;     __device__ __forceinline__ void operator()(const f32x4 (&acc)[2][2][4][2], const GUnit& u, int wr, int wc, int fr, int fq, LAS unsigned char* lds) const {
;     ...
;                     for (int j = 0; j < 4; ++j) { const int g = (int)gp[m][j];
;                         const int oldu = m > 0 ? shl_((int)gp[m > 0 ? m - 1 : 0][j], lane15) : (int)eup[j];
;                         const int ups = __builtin_amdgcn_update_dpp(0, g, 0x111, 0xf, 0xf, true);
;                         const int oldd = m < 3 ? shl_((int)gp[m < 3 ? m + 1 : 3][j], lane0r) : (int)edp[j];
;                         const int dns = __builtin_amdgcn_update_dpp(0, g, 0x101, 0xf, 0xf, true);
;                         UP[j] = (unsigned)(frL == 0 ? oldu : ups); DN[j] = (unsigned)(frL == 15 ? oldd : dns); GG[j] = (unsigned)g; }
;                     const f16x8 uph = __builtin_bit_cast(f16x8, UP), dnh = __builtin_bit_cast(f16x8, DN), ggh = __builtin_bit_cast(f16x8, GG);
;                     f16x2 yv[4];
;                     yv[0] = __builtin_shufflevector(uph, uph, 0, 1) * w0p[0] + __builtin_shufflevector(ggh, ggh, 0, 1) * w1p[0] + __builtin_shufflevector(dnh, dnh, 0, 1) * w2p[0] + bbp[0];
;                     yv[1] = __builtin_shufflevector(uph, uph, 2, 3) * w0p[1] + __builtin_shufflevector(ggh, ggh, 2, 3) * w1p[1] + __builtin_shufflevector(dnh, dnh, 2, 3) * w2p[1] + bbp[1];
;                     yv[2] = __builtin_shufflevector(uph, uph, 4, 5) * w0p[2] + __builtin_shufflevector(ggh, ggh, 4, 5) * w1p[2] + __builtin_shufflevector(dnh, dnh, 4, 5) * w2p[2] + bbp[2];
;                     yv[3] = __builtin_shufflevector(uph, uph, 6, 7) * w0p[3] + __builtin_shufflevector(ggh, ggh, 6, 7) * w1p[3] + __builtin_shufflevector(dnh, dnh, 6, 7) * w2p[3] + bbp[3];
;                     u32x4 o;
; #pragma unroll
;                     for (int n = 0; n < 2; ++n)
; #pragma unroll
;                         for (int q = 0; q < 2; ++q) { const int j = 2 * n + q;
;                             if (m == 0 && c == 0 && frL == 0 && pmod != 0) { const size_t off = (size_t)(u.pm * 2 + 0) * DFF + fb + 4 * n + 2 * q; *(f32x2*)(GB + off) = (f32x2){acc[ai][1][0][n][2 * q], acc[ai][1][0][n][2 * q + 1]}; *(f32x2*)(YP + off) = (f32x2){(float)yv[j][0], (float)yv[j][1]}; *(f32x2*)(VB + off) = (f32x2){acc[ai][0][0][n][2 * q], acc[ai][0][0][n][2 * q + 1]}; }
	v_add_u32_e32 v134, 0x40004, v134
	v_pk_max_f16 v146, v146, 0
	v_pack_b32_f16 v172, v172, v173
	v_pk_fma_f16 v173, v172, s45, v228 op_sel_hi:[1,0,0]
	v_and_b32_e32 v145, 0xfff8fff8, v134
	v_pk_fma_f16 v173, v172, v173, s55 op_sel_hi:[1,1,0]
	v_cvt_pk_f16_f32 v134, v44, v45
	v_pk_fma_f16 v173, v172, v173, s65 op_sel_hi:[1,1,0]
	s_nop 0
	v_pk_fma_f16 v173, v172, v173, s68 op_sel_hi:[1,1,0]
	s_nop 0
	v_pk_mul_f16 v172, v172, v173
	v_pack_b32_f16 v173, v176, v174
	v_pk_mul_f16 v172, v173, v172
	v_pk_mul_f16 v174, v175, s69 op_sel_hi:[1,0]
	v_pk_fma_f16 v146, v147, v172, v146 neg_lo:[1,0,0] neg_hi:[1,0,0]
	v_and_b32_e32 v147, 0x7fff7fff, v135
	v_pk_mul_f16 v134, v134, v146
	v_pk_fma_f16 v146, v147, s36, 1.0 op_sel_hi:[1,0,0]
	v_exp_f16_e32 v175, v174
	v_rcp_f16_e32 v172, v146
	v_rcp_f16_sdwa v173, v146 dst_sel:DWORD dst_unused:UNUSED_PAD src0_sel:WORD_1
	v_exp_f16_sdwa v174, v174 dst_sel:DWORD dst_unused:UNUSED_PAD src0_sel:WORD_1
	v_add_u32_e32 v134, 0x40004, v134
	v_pk_max_f16 v135, v135, 0
	v_pack_b32_f16 v172, v172, v173
	v_pk_fma_f16 v173, v172, s45, v228 op_sel_hi:[1,0,0]
	v_and_b32_e32 v146, 0xfff8fff8, v134
	v_pk_fma_f16 v173, v172, v173, s55 op_sel_hi:[1,1,0]
	v_cvt_pk_f16_f32 v134, v46, v47
	v_pk_fma_f16 v173, v172, v173, s65 op_sel_hi:[1,1,0]
	s_nop 0
	v_pk_fma_f16 v173, v172, v173, s68 op_sel_hi:[1,1,0]
	s_nop 0
	v_pk_mul_f16 v172, v172, v173
	v_pack_b32_f16 v173, v175, v174
	v_pk_mul_f16 v172, v173, v172
	v_mov_b32_dpp v174, v142 row_shl:1 row_mask:0xf bank_mask:0xf bound_ctrl:1
	v_pk_fma_f16 v135, v147, v172, v135 neg_lo:[1,0,0] neg_hi:[1,0,0]
	v_mov_b32_dpp v172, v178 row_ror:1 row_mask:0xf bank_mask:0xf
	v_pk_mul_f16 v134, v134, v135
	v_mov_b32_dpp v173, v143 row_shl:1 row_mask:0xf bank_mask:0xf bound_ctrl:1
	v_add_u32_e32 v134, 0x40004, v134
	v_and_b32_e32 v147, 0xfff8fff8, v134
	v_add_u32_e32 v134, 0x90, v32
	v_mad_i64_i32 v[134:135], s[12:13], v134, s29, v[150:151]
	global_store_dwordx4 v[134:135], v[144:147], off
	s_nop 1
	v_mov_b32_dpp v134, v136 row_ror:15 row_mask:0xf bank_mask:0xf
	v_mov_b32_dpp v145, v179 row_ror:1 row_mask:0xf bank_mask:0xf
	v_mov_b32_dpp v144, v171 row_shl:1 row_mask:0xf bank_mask:0xf bound_ctrl:1
	v_mov_b32_dpp v146, v169 row_shr:1 row_mask:0xf bank_mask:0xf bound_ctrl:1
	v_mov_b32_dpp v135, v171 row_shr:1 row_mask:0xf bank_mask:0xf bound_ctrl:1
	s_waitcnt lgkmcnt(0)
	v_cndmask_b32_e64 v134, v144, v134, s[8:9]
	v_mov_b32_dpp v144, v137 row_ror:15 row_mask:0xf bank_mask:0xf
	s_waitcnt lgkmcnt(0)
	v_cndmask_b32_e64 v145, v146, v145, s[10:11]
	v_mov_b32_dpp v146, v181 row_ror:1 row_mask:0xf bank_mask:0xf
	v_mov_b32_dpp v147, v169 row_shl:1 row_mask:0xf bank_mask:0xf bound_ctrl:1
	v_cndmask_b32_e64 v135, v135, v172, s[10:11]
	s_waitcnt lgkmcnt(0)
	v_cndmask_b32_e64 v144, v147, v144, s[8:9]
	v_mov_b32_dpp v147, v143 row_shr:1 row_mask:0xf bank_mask:0xf bound_ctrl:1
	v_mov_b32_dpp v172, v138 row_ror:15 row_mask:0xf bank_mask:0xf
	s_waitcnt lgkmcnt(0)
	v_cndmask_b32_e64 v146, v147, v146, s[10:11]
	v_mov_b32_dpp v147, v183 row_ror:1 row_mask:0xf bank_mask:0xf
	v_mov_b32_dpp v165, v140 row_ror:15 row_mask:0xf bank_mask:0xf
	v_pk_mul_f16 v135, v164, v135
	s_waitcnt lgkmcnt(0)
	v_cndmask_b32_e64 v172, v173, v172, s[8:9]
	v_mov_b32_dpp v173, v142 row_shr:1 row_mask:0xf bank_mask:0xf bound_ctrl:1
	v_pk_mul_f16 v145, v166, v145
	v_pk_fma_f16 v135, v156, v171, v135
	s_waitcnt lgkmcnt(0)
	v_cndmask_b32_e64 v147, v173, v147, s[10:11]
	v_pk_fma_f16 v145, v158, v169, v145
	v_pk_fma_f16 v134, v163, v134, v135
	v_pk_mul_f16 v147, v170, v147
	v_pk_fma_f16 v144, v161, v144, v145
	v_pk_add_f16 v134, v159, v134
	s_waitcnt lgkmcnt(0)
;     __device__ __forceinline__ void operator()(const f32x4 (&acc)[2][2][4][2], const GUnit& u, int wr, int wc, int fr, int fq, LAS unsigned char* lds) const {
;     ...
;                     for (int j = 0; j < 4; ++j) { const int g = (int)gp[m][j];
;                         const int oldu = m > 0 ? shl_((int)gp[m > 0 ? m - 1 : 0][j], lane15) : (int)eup[j];
;                         const int ups = __builtin_amdgcn_update_dpp(0, g, 0x111, 0xf, 0xf, true);
;                         const int oldd = m < 3 ? shl_((int)gp[m < 3 ? m + 1 : 3][j], lane0r) : (int)edp[j];
;                         const int dns = __builtin_amdgcn_update_dpp(0, g, 0x101, 0xf, 0xf, true);
;                         UP[j] = (unsigned)(frL == 0 ? oldu : ups); DN[j] = (unsigned)(frL == 15 ? oldd : dns); GG[j] = (unsigned)g; }
;                     const f16x8 uph = __builtin_bit_cast(f16x8, UP), dnh = __builtin_bit_cast(f16x8, DN), ggh = __builtin_bit_cast(f16x8, GG);
;                     f16x2 yv[4];
;                     yv[0] = __builtin_shufflevector(uph, uph, 0, 1) * w0p[0] + __builtin_shufflevector(ggh, ggh, 0, 1) * w1p[0] + __builtin_shufflevector(dnh, dnh, 0, 1) * w2p[0] + bbp[0];
;                     yv[1] = __builtin_shufflevector(uph, uph, 2, 3) * w0p[1] + __builtin_shufflevector(ggh, ggh, 2, 3) * w1p[1] + __builtin_shufflevector(dnh, dnh, 2, 3) * w2p[1] + bbp[1];
;                     yv[2] = __builtin_shufflevector(uph, uph, 4, 5) * w0p[2] + __builtin_shufflevector(ggh, ggh, 4, 5) * w1p[2] + __builtin_shufflevector(dnh, dnh, 4, 5) * w2p[2] + bbp[2];
;                     yv[3] = __builtin_shufflevector(uph, uph, 6, 7) * w0p[3] + __builtin_shufflevector(ggh, ggh, 6, 7) * w1p[3] + __builtin_shufflevector(dnh, dnh, 6, 7) * w2p[3] + bbp[3];
;                     u32x4 o;
; #pragma unroll
;                     for (int n = 0; n < 2; ++n)
; #pragma unroll
;                         for (int q = 0; q < 2; ++q) { const int j = 2 * n + q;
;                             if (m == 0 && c == 0 && frL == 0 && pmod != 0) { const size_t off = (size_t)(u.pm * 2 + 0) * DFF + fb + 4 * n + 2 * q; *(f32x2*)(GB + off) = (f32x2){acc[ai][1][0][n][2 * q], acc[ai][1][0][n][2 * q + 1]}; *(f32x2*)(YP + off) = (f32x2){(float)yv[j][0], (float)yv[j][1]}; *(f32x2*)(VB + off) = (f32x2){acc[ai][0][0][n][2 * q], acc[ai][0][0][n][2 * q + 1]}; }
	v_cndmask_b32_e64 v165, v174, v165, s[8:9]
	v_pk_fma_f16 v147, v162, v142, v147
	v_pk_add_f16 v145, v157, v144
	v_and_b32_e32 v144, 0x7fff7fff, v134
	v_pk_fma_f16 v135, v154, v165, v147
	v_pk_fma_f16 v147, v144, s36, 1.0 op_sel_hi:[1,0,0]
	v_pk_mul_f16 v146, v168, v146
	v_rcp_f16_e32 v165, v147
	v_rcp_f16_sdwa v147, v147 dst_sel:DWORD dst_unused:UNUSED_PAD src0_sel:WORD_1
	v_pk_fma_f16 v146, v160, v143, v146
	v_pk_mul_f16 v176, v145, v145
	v_pk_fma_f16 v146, v152, v172, v146
	v_pack_b32_f16 v147, v165, v147
	v_pk_fma_f16 v165, v147, s45, v228 op_sel_hi:[1,0,0]
	v_cvt_pk_f16_f32 v172, v28, v29
	v_pk_fma_f16 v165, v147, v165, s55 op_sel_hi:[1,1,0]
	v_pk_add_f16 v146, v155, v146
	v_pk_fma_f16 v165, v147, v165, s65 op_sel_hi:[1,1,0]
	v_pk_mul_f16 v175, v146, v146
	v_pk_fma_f16 v165, v147, v165, s68 op_sel_hi:[1,1,0]
	v_pk_add_f16 v135, v153, v135
	v_pk_mul_f16 v147, v147, v165
	v_pk_mul_f16 v165, v134, v134
	v_pk_max_f16 v134, v134, 0
	v_pk_mul_f16 v165, v165, s69 op_sel_hi:[1,0]
	v_pk_mul_f16 v174, v135, v135
	v_exp_f16_e32 v173, v165
	v_exp_f16_sdwa v165, v165 dst_sel:DWORD dst_unused:UNUSED_PAD src0_sel:WORD_1
	v_mov_b32_dpp v143, v143 row_ror:1 row_mask:0xf bank_mask:0xf
	v_mov_b32_dpp v142, v142 row_ror:1 row_mask:0xf bank_mask:0xf
	v_pack_b32_f16 v165, v173, v165
	v_pk_mul_f16 v147, v165, v147
	v_pk_mul_f16 v173, v176, s69 op_sel_hi:[1,0]
	v_pk_fma_f16 v134, v144, v147, v134 neg_lo:[1,0,0] neg_hi:[1,0,0]
	v_and_b32_e32 v147, 0x7fff7fff, v145
	v_pk_fma_f16 v144, v147, s36, 1.0 op_sel_hi:[1,0,0]
	v_pk_mul_f16 v134, v172, v134
	v_rcp_f16_e32 v165, v144
	v_rcp_f16_sdwa v172, v144 dst_sel:DWORD dst_unused:UNUSED_PAD src0_sel:WORD_1
	v_exp_f16_e32 v176, v173
	v_exp_f16_sdwa v173, v173 dst_sel:DWORD dst_unused:UNUSED_PAD src0_sel:WORD_1
	v_add_u32_e32 v134, 0x40004, v134
	v_pack_b32_f16 v165, v165, v172
	v_pk_fma_f16 v172, v165, s45, v228 op_sel_hi:[1,0,0]
	v_pk_max_f16 v145, v145, 0
	v_pk_fma_f16 v172, v165, v172, s55 op_sel_hi:[1,1,0]
	v_and_b32_e32 v144, 0xfff8fff8, v134
	v_pk_fma_f16 v172, v165, v172, s65 op_sel_hi:[1,1,0]
	v_cvt_pk_f16_f32 v134, v30, v31
	v_pk_fma_f16 v172, v165, v172, s68 op_sel_hi:[1,1,0]
	s_nop 0
	v_pk_mul_f16 v165, v165, v172
	v_pack_b32_f16 v172, v176, v173
	v_pk_mul_f16 v165, v172, v165
	v_pk_mul_f16 v173, v175, s69 op_sel_hi:[1,0]
	v_pk_fma_f16 v145, v147, v165, v145 neg_lo:[1,0,0] neg_hi:[1,0,0]
	v_and_b32_e32 v147, 0x7fff7fff, v146
	v_pk_mul_f16 v134, v134, v145
	v_pk_fma_f16 v145, v147, s36, 1.0 op_sel_hi:[1,0,0]
	v_exp_f16_e32 v175, v173
	v_rcp_f16_e32 v165, v145
	v_rcp_f16_sdwa v172, v145 dst_sel:DWORD dst_unused:UNUSED_PAD src0_sel:WORD_1
	v_exp_f16_sdwa v173, v173 dst_sel:DWORD dst_unused:UNUSED_PAD src0_sel:WORD_1
	v_add_u32_e32 v134, 0x40004, v134
	v_pk_max_f16 v146, v146, 0
	v_pack_b32_f16 v165, v165, v172
	v_pk_fma_f16 v172, v165, s45, v228 op_sel_hi:[1,0,0]
	v_and_b32_e32 v145, 0xfff8fff8, v134
	v_pk_fma_f16 v172, v165, v172, s55 op_sel_hi:[1,1,0]
	v_cvt_pk_f16_f32 v134, v24, v25
	v_pk_fma_f16 v172, v165, v172, s65 op_sel_hi:[1,1,0]
	s_nop 0
	v_pk_fma_f16 v172, v165, v172, s68 op_sel_hi:[1,1,0]
	s_nop 0
	v_pk_mul_f16 v165, v165, v172
	v_pack_b32_f16 v172, v175, v173
	v_pk_mul_f16 v165, v172, v165
	v_pk_mul_f16 v173, v174, s69 op_sel_hi:[1,0]
	v_pk_fma_f16 v146, v147, v165, v146 neg_lo:[1,0,0] neg_hi:[1,0,0]
	v_and_b32_e32 v147, 0x7fff7fff, v135
	v_pk_mul_f16 v134, v134, v146
	v_pk_fma_f16 v146, v147, s36, 1.0 op_sel_hi:[1,0,0]
	v_exp_f16_e32 v174, v173
	v_rcp_f16_e32 v165, v146
	v_rcp_f16_sdwa v172, v146 dst_sel:DWORD dst_unused:UNUSED_PAD src0_sel:WORD_1
	v_exp_f16_sdwa v173, v173 dst_sel:DWORD dst_unused:UNUSED_PAD src0_sel:WORD_1
	v_add_u32_e32 v134, 0x40004, v134
	v_pk_max_f16 v135, v135, 0
	v_pack_b32_f16 v165, v165, v172
	v_pk_fma_f16 v172, v165, s45, v228 op_sel_hi:[1,0,0]
	v_and_b32_e32 v146, 0xfff8fff8, v134
	v_pk_fma_f16 v172, v165, v172, s55 op_sel_hi:[1,1,0]
	v_cvt_pk_f16_f32 v134, v26, v27
	v_pk_fma_f16 v172, v165, v172, s65 op_sel_hi:[1,1,0]
	s_nop 0
	v_pk_fma_f16 v172, v165, v172, s68 op_sel_hi:[1,1,0]
	s_nop 0
	v_pk_mul_f16 v165, v165, v172
	v_pack_b32_f16 v172, v174, v173
	v_pk_mul_f16 v165, v172, v165
	s_nop 0
	v_pk_fma_f16 v135, v147, v165, v135 neg_lo:[1,0,0] neg_hi:[1,0,0]
	v_mov_b32_dpp v165, v171 row_ror:1 row_mask:0xf bank_mask:0xf
	v_pk_mul_f16 v134, v134, v135
	s_nop 0
	v_add_u32_e32 v134, 0x40004, v134
	v_and_b32_e32 v147, 0xfff8fff8, v134
	v_add_u32_e32 v134, 0xa0, v32
	v_mad_i64_i32 v[134:135], s[12:13], v134, s29, v[150:151]
	global_store_dwordx4 v[134:135], v[144:147], off
	s_nop 1
	v_mov_b32_dpp v144, v169 row_ror:1 row_mask:0xf bank_mask:0xf
	v_mov_b32_dpp v135, v136 row_shl:1 row_mask:0xf bank_mask:0xf bound_ctrl:1
	v_cndmask_b32_e64 v135, v135, v141, s[8:9]
	v_mov_b32_dpp v141, v137 row_shr:1 row_mask:0xf bank_mask:0xf bound_ctrl:1
	v_mov_b32_dpp v134, v136 row_shr:1 row_mask:0xf bank_mask:0xf bound_ctrl:1
	s_waitcnt lgkmcnt(0)
	v_cndmask_b32_e64 v141, v141, v144, s[10:11]
	v_mov_b32_dpp v144, v138 row_shr:1 row_mask:0xf bank_mask:0xf bound_ctrl:1
	v_mov_b32_dpp v145, v137 row_shl:1 row_mask:0xf bank_mask:0xf bound_ctrl:1
	v_cndmask_b32_e64 v143, v144, v143, s[10:11]
	v_mov_b32_dpp v144, v140 row_shr:1 row_mask:0xf bank_mask:0xf bound_ctrl:1
	v_cndmask_b32_e64 v134, v134, v165, s[10:11]
	v_cndmask_b32_e64 v139, v145, v139, s[8:9]
	v_mov_b32_dpp v145, v138 row_shl:1 row_mask:0xf bank_mask:0xf bound_ctrl:1
	v_cndmask_b32_e64 v142, v144, v142, s[10:11]
	v_readlane_b32 s10, v251, 61
	v_cndmask_b32_e64 v133, v145, v133, s[8:9]
	v_mov_b32_dpp v145, v140 row_shl:1 row_mask:0xf bank_mask:0xf bound_ctrl:1
	v_pk_mul_f16 v134, v164, v134
	v_pk_mul_f16 v141, v166, v141
	v_pk_mul_f16 v143, v168, v143
	v_pk_mul_f16 v142, v170, v142
	v_readlane_b32 s11, v251, 62
	v_cndmask_b32_e64 v132, v145, v132, s[8:9]
	v_pk_fma_f16 v140, v162, v140, v142
	v_pk_fma_f16 v138, v160, v138, v143
	v_pk_fma_f16 v137, v158, v137, v141
	v_pk_fma_f16 v134, v156, v136, v134
	s_and_b64 s[8:9], s[10:11], s[8:9]
	v_pk_fma_f16 v135, v163, v135, v134
	v_pk_fma_f16 v134, v161, v139, v137
	v_pk_fma_f16 v133, v152, v133, v138
	v_pk_fma_f16 v132, v154, v132, v140
	s_and_b64 s[8:9], s[8:9], s[80:81]
	v_pk_add_f16 v132, v153, v132
	v_pk_add_f16 v133, v155, v133
	v_pk_add_f16 v134, v157, v134
	v_pk_add_f16 v135, v159, v135
	s_xor_b64 s[8:9], s[8:9], -1
	s_and_saveexec_b64 s[10:11], s[8:9]
	s_xor_b64 s[10:11], exec, s[10:11]
	s_andn2_saveexec_b64 s[10:11], s[10:11]
	s_cbranch_execnz .LBB0_423
	s_or_b64 exec, exec, s[10:11]
	s_and_saveexec_b64 s[10:11], s[8:9]
	s_xor_b64 s[10:11], exec, s[10:11]
	s_cbranch_execnz .LBB0_424
